# IEEE f32 division in gelu/sigmoid GEMM epilogues (S5 output, GLU) replaced by v_rcp_f32 (+mul)
# speedup vs baseline: 1.0081x; 1.0081x over previous
.LBB0_920:
	v_mul_f32_e32 v151, 0x3d372713, v124
	v_mul_f32_e32 v151, v124, v151
	v_fma_f32 v151, v124, v151, v124
	v_mul_f32_e32 v151, 0x3f4c422a, v151
	v_add_f32_e32 v151, v151, v151
	v_mul_f32_e32 v151, 0x3fb8aa3b, v151
	v_exp_f32_e32 v151, v151
	s_mul_i32 s9, s24, 0xffffd00
	s_lshl_b32 s25, s25, 12
	v_add_u32_e32 v152, s9, v144
	v_add_f32_e32 v153, 1.0, v151
	v_lshl_add_u32 v151, v152, 4, s25
	s_lshl_b32 s18, s24, 4
	v_mul_f32_e32 v124, 0.5, v124
	v_mul_f32_e32 v154, 0x3d372713, v125
	v_mul_f32_e32 v154, v125, v154
	v_fma_f32 v154, v125, v154, v125
	v_mul_f32_e32 v154, 0x3f4c422a, v154
	v_add_f32_e32 v154, v154, v154
	v_mul_f32_e32 v154, 0x3fb8aa3b, v154
	v_exp_f32_e32 v154, v154
	v_rcp_f32_e32 v152, v153
	s_nop 0
	v_add_f32_e32 v152, v152, v152
	v_sub_f32_e32 v152, 1.0, v152
	v_add_f32_e32 v153, 1.0, v154
	v_add_f32_e32 v152, 1.0, v152
	v_mul_f32_e32 v124, v124, v152
	v_mul_f32_e32 v125, 0.5, v125
	v_mul_f32_e32 v154, 0x3d372713, v126
	v_mul_f32_e32 v154, v126, v154
	v_fma_f32 v154, v126, v154, v126
	v_mul_f32_e32 v154, 0x3f4c422a, v154
	v_add_f32_e32 v154, v154, v154
	v_mul_f32_e32 v154, 0x3fb8aa3b, v154
	v_exp_f32_e32 v154, v154
	v_rcp_f32_e32 v152, v153
	s_nop 0
	v_add_f32_e32 v152, v152, v152
	v_sub_f32_e32 v152, 1.0, v152
	v_add_f32_e32 v153, 1.0, v154
	v_add_f32_e32 v152, 1.0, v152
	v_mul_f32_e32 v125, v125, v152
	v_cvt_pk_bf16_f32 v124, v124, v125
	v_mul_f32_e32 v154, 0x3d372713, v127
	v_mul_f32_e32 v154, v127, v154
	v_fma_f32 v154, v127, v154, v127
	v_mul_f32_e32 v154, 0x3f4c422a, v154
	v_add_f32_e32 v154, v154, v154
	v_mul_f32_e32 v154, 0x3fb8aa3b, v154
	v_exp_f32_e32 v154, v154
	v_rcp_f32_e32 v125, v153
	s_nop 0
	v_add_f32_e32 v125, v125, v125
	v_sub_f32_e32 v125, 1.0, v125
	v_add_f32_e32 v152, 1.0, v154
	v_mul_f32_e32 v126, 0.5, v126
	v_add_f32_e32 v125, 1.0, v125
	v_mul_f32_e32 v125, v126, v125
	v_mul_f32_e32 v153, 0x3d372713, v120
	v_mul_f32_e32 v153, v120, v153
	v_fma_f32 v153, v120, v153, v120
	v_mul_f32_e32 v153, 0x3f4c422a, v153
	v_add_f32_e32 v153, v153, v153
	v_mul_f32_e32 v153, 0x3fb8aa3b, v153
	v_exp_f32_e32 v153, v153
	v_rcp_f32_e32 v126, v152
	s_nop 0
	v_add_f32_e32 v126, v126, v126
	v_sub_f32_e32 v126, 1.0, v126
	v_add_f32_e32 v152, 1.0, v153
	v_mul_f32_e32 v127, 0.5, v127
	v_add_f32_e32 v126, 1.0, v126
	v_mul_f32_e32 v126, v127, v126
	v_cvt_pk_bf16_f32 v125, v125, v126
	v_mul_f32_e32 v153, 0x3d372713, v121
	v_mul_f32_e32 v153, v121, v153
	v_fma_f32 v153, v121, v153, v121
	v_mul_f32_e32 v153, 0x3f4c422a, v153
	v_add_f32_e32 v153, v153, v153
	v_mul_f32_e32 v153, 0x3fb8aa3b, v153
	v_exp_f32_e32 v153, v153
	v_rcp_f32_e32 v126, v152
	s_nop 0
	v_add_f32_e32 v126, v126, v126
	v_sub_f32_e32 v126, 1.0, v126
	v_add_f32_e32 v127, 1.0, v153
	v_mul_f32_e32 v120, 0.5, v120
	v_add_f32_e32 v126, 1.0, v126
	v_mul_f32_e32 v120, v120, v126
	v_mul_f32_e32 v152, 0x3d372713, v122
	v_mul_f32_e32 v152, v122, v152
	v_fma_f32 v152, v122, v152, v122
	v_mul_f32_e32 v152, 0x3f4c422a, v152
	v_add_f32_e32 v152, v152, v152
	v_mul_f32_e32 v152, 0x3fb8aa3b, v152
	v_exp_f32_e32 v152, v152
	v_rcp_f32_e32 v126, v127
	s_nop 0
	v_add_f32_e32 v126, v126, v126
	v_sub_f32_e32 v126, 1.0, v126
	v_add_f32_e32 v127, 1.0, v152
	v_mul_f32_e32 v121, 0.5, v121
	v_add_f32_e32 v126, 1.0, v126
	v_mul_f32_e32 v121, v121, v126
	v_cvt_pk_bf16_f32 v126, v120, v121
	v_mul_f32_e32 v152, 0x3d372713, v123
	v_mul_f32_e32 v152, v123, v152
	v_fma_f32 v152, v123, v152, v123
	v_mul_f32_e32 v152, 0x3f4c422a, v152
	v_add_f32_e32 v152, v152, v152
	v_mul_f32_e32 v152, 0x3fb8aa3b, v152
	v_exp_f32_e32 v152, v152
	v_rcp_f32_e32 v120, v127
	s_nop 0
	v_add_f32_e32 v120, v120, v120
	v_sub_f32_e32 v120, 1.0, v120
	v_add_f32_e32 v121, 1.0, v152
	v_mul_f32_e32 v122, 0.5, v122
	v_add_f32_e32 v120, 1.0, v120
	v_mul_f32_e32 v120, v122, v120
	v_rcp_f32_e32 v121, v121
	s_nop 0
	v_add_f32_e32 v121, v121, v121
	v_sub_f32_e32 v121, 1.0, v121
	v_mul_f32_e32 v122, 0.5, v123
	v_add_f32_e32 v121, 1.0, v121
	v_mul_f32_e32 v121, v122, v121
	v_mul_f32_e32 v122, 0x3d372713, v116
	v_mul_f32_e32 v122, v116, v122
	v_fma_f32 v122, v116, v122, v116
	v_mul_f32_e32 v122, 0x3f4c422a, v122
	v_add_f32_e32 v122, v122, v122
	v_mul_f32_e32 v122, 0x3fb8aa3b, v122
	v_exp_f32_e32 v122, v122
	v_cvt_pk_bf16_f32 v127, v120, v121
	v_add_u32_e32 v120, v151, v146
	v_ashrrev_i32_e32 v121, 31, v120
	v_add_f32_e32 v122, 1.0, v122
	s_ashr_i32 s19, s18, 31
	v_lshlrev_b64 v[120:121], 10, v[120:121]
	v_lshl_add_u64 v[120:121], s[60:61], 0, v[120:121]
	s_lshl_b64 s[18:19], s[18:19], 1
	v_lshl_add_u64 v[120:121], v[120:121], 0, s[18:19]
	v_lshl_add_u64 v[120:121], v[120:121], 0, v[136:137]
	global_store_dwordx4 v[120:121], v[124:127], off
	v_mul_f32_e32 v123, 0x3d372713, v117
	v_mul_f32_e32 v123, v117, v123
	v_fma_f32 v123, v117, v123, v117
	v_mul_f32_e32 v123, 0x3f4c422a, v123
	v_add_f32_e32 v123, v123, v123
	v_mul_f32_e32 v123, 0x3fb8aa3b, v123
	v_exp_f32_e32 v123, v123
	v_rcp_f32_e32 v120, v122
	s_nop 0
	v_add_f32_e32 v120, v120, v120
	v_sub_f32_e32 v120, 1.0, v120
	v_add_f32_e32 v121, 1.0, v123
	v_mul_f32_e32 v116, 0.5, v116
	v_add_f32_e32 v120, 1.0, v120
	v_mul_f32_e32 v116, v116, v120
	v_mul_f32_e32 v122, 0x3d372713, v118
	v_mul_f32_e32 v122, v118, v122
	v_fma_f32 v122, v118, v122, v118
	v_mul_f32_e32 v122, 0x3f4c422a, v122
	v_add_f32_e32 v122, v122, v122
	v_mul_f32_e32 v122, 0x3fb8aa3b, v122
	v_exp_f32_e32 v122, v122
	v_rcp_f32_e32 v120, v121
	s_nop 0
	v_add_f32_e32 v120, v120, v120
	v_sub_f32_e32 v120, 1.0, v120
	v_add_f32_e32 v121, 1.0, v122
	v_mul_f32_e32 v117, 0.5, v117
	v_add_f32_e32 v120, 1.0, v120
	v_mul_f32_e32 v117, v117, v120
	v_cvt_pk_bf16_f32 v116, v116, v117
	v_mul_f32_e32 v122, 0x3d372713, v119
	v_mul_f32_e32 v122, v119, v122
	v_fma_f32 v122, v119, v122, v119
	v_mul_f32_e32 v122, 0x3f4c422a, v122
	v_add_f32_e32 v122, v122, v122
	v_mul_f32_e32 v122, 0x3fb8aa3b, v122
	v_exp_f32_e32 v122, v122
	v_rcp_f32_e32 v117, v121
	s_nop 0
	v_add_f32_e32 v117, v117, v117
	v_sub_f32_e32 v117, 1.0, v117
	v_add_f32_e32 v120, 1.0, v122
	v_mul_f32_e32 v118, 0.5, v118
	v_add_f32_e32 v117, 1.0, v117
	v_mul_f32_e32 v117, v118, v117
	v_mul_f32_e32 v121, 0x3d372713, v112
	v_mul_f32_e32 v121, v112, v121
	v_fma_f32 v121, v112, v121, v112
	v_mul_f32_e32 v121, 0x3f4c422a, v121
	v_add_f32_e32 v121, v121, v121
	v_mul_f32_e32 v121, 0x3fb8aa3b, v121
	v_exp_f32_e32 v121, v121
	v_rcp_f32_e32 v118, v120
	s_nop 0
	v_add_f32_e32 v118, v118, v118
	v_sub_f32_e32 v118, 1.0, v118
	v_add_f32_e32 v120, 1.0, v121
	v_mul_f32_e32 v119, 0.5, v119
	v_add_f32_e32 v118, 1.0, v118
	v_mul_f32_e32 v118, v119, v118
	v_cvt_pk_bf16_f32 v117, v117, v118
	v_mul_f32_e32 v121, 0x3d372713, v113
	v_mul_f32_e32 v121, v113, v121
	v_fma_f32 v121, v113, v121, v113
	v_mul_f32_e32 v121, 0x3f4c422a, v121
	v_add_f32_e32 v121, v121, v121
	v_mul_f32_e32 v121, 0x3fb8aa3b, v121
	v_exp_f32_e32 v121, v121
	v_rcp_f32_e32 v118, v120
	s_nop 0
	v_add_f32_e32 v118, v118, v118
	v_sub_f32_e32 v118, 1.0, v118
	v_add_f32_e32 v119, 1.0, v121
	v_mul_f32_e32 v112, 0.5, v112
	v_add_f32_e32 v118, 1.0, v118
	v_mul_f32_e32 v112, v112, v118
	v_mul_f32_e32 v120, 0x3d372713, v114
	v_mul_f32_e32 v120, v114, v120
	v_fma_f32 v120, v114, v120, v114
	v_mul_f32_e32 v120, 0x3f4c422a, v120
	v_add_f32_e32 v120, v120, v120
	v_mul_f32_e32 v120, 0x3fb8aa3b, v120
	v_exp_f32_e32 v120, v120
	v_rcp_f32_e32 v118, v119
	s_nop 0
	v_add_f32_e32 v118, v118, v118
	v_sub_f32_e32 v118, 1.0, v118
	v_add_f32_e32 v119, 1.0, v120
	v_mul_f32_e32 v113, 0.5, v113
	v_add_f32_e32 v118, 1.0, v118
	v_mul_f32_e32 v113, v113, v118
	v_cvt_pk_bf16_f32 v118, v112, v113
	v_mul_f32_e32 v120, 0x3d372713, v115
	v_mul_f32_e32 v120, v115, v120
	v_fma_f32 v120, v115, v120, v115
	v_mul_f32_e32 v120, 0x3f4c422a, v120
	v_add_f32_e32 v120, v120, v120
	v_mul_f32_e32 v120, 0x3fb8aa3b, v120
	v_exp_f32_e32 v120, v120
	v_rcp_f32_e32 v112, v119
	s_nop 0
	v_add_f32_e32 v112, v112, v112
	v_sub_f32_e32 v112, 1.0, v112
	v_add_f32_e32 v113, 1.0, v120
	v_mul_f32_e32 v114, 0.5, v114
	v_add_f32_e32 v112, 1.0, v112
	v_mul_f32_e32 v112, v114, v112
	v_rcp_f32_e32 v113, v113
	s_nop 0
	v_add_f32_e32 v113, v113, v113
	v_sub_f32_e32 v113, 1.0, v113
	v_mul_f32_e32 v114, 0.5, v115
	v_add_f32_e32 v113, 1.0, v113
	v_mul_f32_e32 v113, v114, v113
	v_mul_f32_e32 v114, 0x3d372713, v108
	v_mul_f32_e32 v114, v108, v114
	v_fma_f32 v114, v108, v114, v108
	v_mul_f32_e32 v114, 0x3f4c422a, v114
	v_add_f32_e32 v114, v114, v114
	v_mul_f32_e32 v114, 0x3fb8aa3b, v114
	v_exp_f32_e32 v114, v114
	v_cvt_pk_bf16_f32 v119, v112, v113
	v_add_u32_e32 v112, v151, v147
	v_ashrrev_i32_e32 v113, 31, v112
	v_add_f32_e32 v114, 1.0, v114
	v_lshlrev_b64 v[112:113], 10, v[112:113]
	v_lshl_add_u64 v[112:113], s[60:61], 0, v[112:113]
	v_lshl_add_u64 v[112:113], v[112:113], 0, s[18:19]
	v_lshl_add_u64 v[112:113], v[112:113], 0, v[136:137]
	global_store_dwordx4 v[112:113], v[116:119], off
	v_mul_f32_e32 v115, 0x3d372713, v109
	v_mul_f32_e32 v115, v109, v115
	v_fma_f32 v115, v109, v115, v109
	v_mul_f32_e32 v115, 0x3f4c422a, v115
	v_add_f32_e32 v115, v115, v115
	v_mul_f32_e32 v115, 0x3fb8aa3b, v115
	v_exp_f32_e32 v115, v115
	v_rcp_f32_e32 v113, v114
	s_nop 0
	v_add_f32_e32 v113, v113, v113
	v_sub_f32_e32 v113, 1.0, v113
	v_add_f32_e32 v114, 1.0, v115
	v_mul_f32_e32 v108, 0.5, v108
	v_add_f32_e32 v113, 1.0, v113
	v_mul_f32_e32 v108, v108, v113
	v_mul_f32_e32 v115, 0x3d372713, v110
	v_mul_f32_e32 v115, v110, v115
	v_fma_f32 v115, v110, v115, v110
	v_mul_f32_e32 v115, 0x3f4c422a, v115
	v_add_f32_e32 v115, v115, v115
	v_mul_f32_e32 v115, 0x3fb8aa3b, v115
	v_exp_f32_e32 v115, v115
	v_rcp_f32_e32 v113, v114
	s_nop 0
	v_add_f32_e32 v113, v113, v113
	v_sub_f32_e32 v113, 1.0, v113
	v_add_f32_e32 v114, 1.0, v115
	v_mul_f32_e32 v109, 0.5, v109
	v_add_f32_e32 v113, 1.0, v113
	v_mul_f32_e32 v109, v109, v113
	v_cvt_pk_bf16_f32 v108, v108, v109
	v_mul_f32_e32 v115, 0x3d372713, v111
	v_mul_f32_e32 v115, v111, v115
	v_fma_f32 v115, v111, v115, v111
	v_mul_f32_e32 v115, 0x3f4c422a, v115
	v_add_f32_e32 v115, v115, v115
	v_mul_f32_e32 v115, 0x3fb8aa3b, v115
	v_exp_f32_e32 v115, v115
	v_rcp_f32_e32 v109, v114
	s_nop 0
	v_add_f32_e32 v109, v109, v109
	v_sub_f32_e32 v109, 1.0, v109
	v_add_f32_e32 v113, 1.0, v115
	v_mul_f32_e32 v110, 0.5, v110
	v_add_f32_e32 v109, 1.0, v109
	v_mul_f32_e32 v109, v110, v109
	v_mul_f32_e32 v114, 0x3d372713, v104
	v_mul_f32_e32 v114, v104, v114
	v_fma_f32 v114, v104, v114, v104
	v_mul_f32_e32 v114, 0x3f4c422a, v114
	v_add_f32_e32 v114, v114, v114
	v_mul_f32_e32 v114, 0x3fb8aa3b, v114
	v_exp_f32_e32 v114, v114
	v_rcp_f32_e32 v110, v113
	s_nop 0
	v_add_f32_e32 v110, v110, v110
	v_sub_f32_e32 v110, 1.0, v110
	v_add_f32_e32 v113, 1.0, v114
	v_mul_f32_e32 v111, 0.5, v111
	v_add_f32_e32 v110, 1.0, v110
	v_mul_f32_e32 v110, v111, v110
	v_cvt_pk_bf16_f32 v109, v109, v110
	v_mul_f32_e32 v114, 0x3d372713, v105
	v_mul_f32_e32 v114, v105, v114
	v_fma_f32 v114, v105, v114, v105
	v_mul_f32_e32 v114, 0x3f4c422a, v114
	v_add_f32_e32 v114, v114, v114
	v_mul_f32_e32 v114, 0x3fb8aa3b, v114
	v_exp_f32_e32 v114, v114
	v_rcp_f32_e32 v110, v113
	s_nop 0
	v_add_f32_e32 v110, v110, v110
	v_sub_f32_e32 v110, 1.0, v110
	v_add_f32_e32 v111, 1.0, v114
	v_mul_f32_e32 v104, 0.5, v104
	v_add_f32_e32 v110, 1.0, v110
	v_mul_f32_e32 v104, v104, v110
	v_mul_f32_e32 v113, 0x3d372713, v106
	v_mul_f32_e32 v113, v106, v113
	v_fma_f32 v113, v106, v113, v106
	v_mul_f32_e32 v113, 0x3f4c422a, v113
	v_add_f32_e32 v113, v113, v113
	v_mul_f32_e32 v113, 0x3fb8aa3b, v113
	v_exp_f32_e32 v113, v113
	v_rcp_f32_e32 v110, v111
	s_nop 0
	v_add_f32_e32 v110, v110, v110
	v_sub_f32_e32 v110, 1.0, v110
	v_add_f32_e32 v111, 1.0, v113
	v_mul_f32_e32 v105, 0.5, v105
	v_add_f32_e32 v110, 1.0, v110
	v_mul_f32_e32 v105, v105, v110
	v_cvt_pk_bf16_f32 v110, v104, v105
	v_mul_f32_e32 v113, 0x3d372713, v107
	v_mul_f32_e32 v113, v107, v113
	v_fma_f32 v113, v107, v113, v107
	v_mul_f32_e32 v113, 0x3f4c422a, v113
	v_add_f32_e32 v113, v113, v113
	v_mul_f32_e32 v113, 0x3fb8aa3b, v113
	v_exp_f32_e32 v113, v113
	v_rcp_f32_e32 v104, v111
	s_nop 0
	v_add_f32_e32 v104, v104, v104
	v_sub_f32_e32 v104, 1.0, v104
	v_add_f32_e32 v105, 1.0, v113
	v_mul_f32_e32 v106, 0.5, v106
	v_add_f32_e32 v104, 1.0, v104
	v_mul_f32_e32 v104, v106, v104
	v_rcp_f32_e32 v105, v105
	s_nop 0
	v_add_f32_e32 v105, v105, v105
	v_sub_f32_e32 v105, 1.0, v105
	v_mul_f32_e32 v106, 0.5, v107
	v_add_f32_e32 v105, 1.0, v105
	v_mul_f32_e32 v105, v106, v105
	v_cvt_pk_bf16_f32 v111, v104, v105
	v_mul_f32_e32 v105, 0x3d372713, v100
	v_mul_f32_e32 v105, v100, v105
	v_fma_f32 v105, v100, v105, v100
	v_mul_f32_e32 v105, 0x3f4c422a, v105
	v_add_f32_e32 v105, v105, v105
	v_mul_f32_e32 v105, 0x3fb8aa3b, v105
	v_exp_f32_e32 v106, v105
	v_or_b32_e32 v112, 0x100, v151
	v_add_u32_e32 v104, v112, v146
	v_ashrrev_i32_e32 v105, 31, v104
	v_add_f32_e32 v106, 1.0, v106
	v_lshlrev_b64 v[104:105], 10, v[104:105]
	v_lshl_add_u64 v[104:105], s[60:61], 0, v[104:105]
	v_lshl_add_u64 v[104:105], v[104:105], 0, s[18:19]
	v_lshl_add_u64 v[104:105], v[104:105], 0, v[136:137]
	global_store_dwordx4 v[104:105], v[108:111], off
	v_mul_f32_e32 v107, 0x3d372713, v101
	v_mul_f32_e32 v107, v101, v107
	v_fma_f32 v107, v101, v107, v101
	v_mul_f32_e32 v107, 0x3f4c422a, v107
	v_add_f32_e32 v107, v107, v107
	v_mul_f32_e32 v107, 0x3fb8aa3b, v107
	v_exp_f32_e32 v107, v107
	v_rcp_f32_e32 v104, v106
	s_nop 0
	v_add_f32_e32 v104, v104, v104
	v_sub_f32_e32 v104, 1.0, v104
	v_add_f32_e32 v105, 1.0, v107
	v_mul_f32_e32 v100, 0.5, v100
	v_add_f32_e32 v104, 1.0, v104
	v_mul_f32_e32 v100, v100, v104
	v_mul_f32_e32 v106, 0x3d372713, v102
	v_mul_f32_e32 v106, v102, v106
	v_fma_f32 v106, v102, v106, v102
	v_mul_f32_e32 v106, 0x3f4c422a, v106
	v_add_f32_e32 v106, v106, v106
	v_mul_f32_e32 v106, 0x3fb8aa3b, v106
	v_exp_f32_e32 v106, v106
	v_rcp_f32_e32 v104, v105
	s_nop 0
	v_add_f32_e32 v104, v104, v104
	v_sub_f32_e32 v104, 1.0, v104
	v_add_f32_e32 v105, 1.0, v106
	v_mul_f32_e32 v101, 0.5, v101
	v_add_f32_e32 v104, 1.0, v104
	v_mul_f32_e32 v101, v101, v104
	v_cvt_pk_bf16_f32 v100, v100, v101
	v_mul_f32_e32 v106, 0x3d372713, v103
	v_mul_f32_e32 v106, v103, v106
	v_fma_f32 v106, v103, v106, v103
	v_mul_f32_e32 v106, 0x3f4c422a, v106
	v_add_f32_e32 v106, v106, v106
	v_mul_f32_e32 v106, 0x3fb8aa3b, v106
	v_exp_f32_e32 v106, v106
	v_rcp_f32_e32 v101, v105
	s_nop 0
	v_add_f32_e32 v101, v101, v101
	v_sub_f32_e32 v101, 1.0, v101
	v_add_f32_e32 v104, 1.0, v106
	v_mul_f32_e32 v102, 0.5, v102
	v_add_f32_e32 v101, 1.0, v101
	v_mul_f32_e32 v101, v102, v101
	v_mul_f32_e32 v105, 0x3d372713, v96
	v_mul_f32_e32 v105, v96, v105
	v_fma_f32 v105, v96, v105, v96
	v_mul_f32_e32 v105, 0x3f4c422a, v105
	v_add_f32_e32 v105, v105, v105
	v_mul_f32_e32 v105, 0x3fb8aa3b, v105
	v_exp_f32_e32 v105, v105
	v_rcp_f32_e32 v102, v104
	s_nop 0
	v_add_f32_e32 v102, v102, v102
	v_sub_f32_e32 v102, 1.0, v102
	v_add_f32_e32 v104, 1.0, v105
	v_mul_f32_e32 v103, 0.5, v103
	v_add_f32_e32 v102, 1.0, v102
	v_mul_f32_e32 v102, v103, v102
	v_cvt_pk_bf16_f32 v101, v101, v102
	v_mul_f32_e32 v105, 0x3d372713, v97
	v_mul_f32_e32 v105, v97, v105
	v_fma_f32 v105, v97, v105, v97
	v_mul_f32_e32 v105, 0x3f4c422a, v105
	v_add_f32_e32 v105, v105, v105
	v_mul_f32_e32 v105, 0x3fb8aa3b, v105
	v_exp_f32_e32 v105, v105
	v_rcp_f32_e32 v102, v104
	s_nop 0
	v_add_f32_e32 v102, v102, v102
	v_sub_f32_e32 v102, 1.0, v102
	v_add_f32_e32 v103, 1.0, v105
	v_mul_f32_e32 v96, 0.5, v96
	v_add_f32_e32 v102, 1.0, v102
	v_mul_f32_e32 v96, v96, v102
	v_mul_f32_e32 v104, 0x3d372713, v98
	v_mul_f32_e32 v104, v98, v104
	v_fma_f32 v104, v98, v104, v98
	v_mul_f32_e32 v104, 0x3f4c422a, v104
	v_add_f32_e32 v104, v104, v104
	v_mul_f32_e32 v104, 0x3fb8aa3b, v104
	v_exp_f32_e32 v104, v104
	v_rcp_f32_e32 v102, v103
	s_nop 0
	v_add_f32_e32 v102, v102, v102
	v_sub_f32_e32 v102, 1.0, v102
	v_add_f32_e32 v103, 1.0, v104
	v_mul_f32_e32 v97, 0.5, v97
	v_add_f32_e32 v102, 1.0, v102
	v_mul_f32_e32 v97, v97, v102
	v_cvt_pk_bf16_f32 v102, v96, v97
	v_mul_f32_e32 v104, 0x3d372713, v99
	v_mul_f32_e32 v104, v99, v104
	v_fma_f32 v104, v99, v104, v99
	v_mul_f32_e32 v104, 0x3f4c422a, v104
	v_add_f32_e32 v104, v104, v104
	v_mul_f32_e32 v104, 0x3fb8aa3b, v104
	v_exp_f32_e32 v104, v104
	v_rcp_f32_e32 v96, v103
	s_nop 0
	v_add_f32_e32 v96, v96, v96
	v_sub_f32_e32 v96, 1.0, v96
	v_add_f32_e32 v97, 1.0, v104
	v_mul_f32_e32 v98, 0.5, v98
	v_add_f32_e32 v96, 1.0, v96
	v_mul_f32_e32 v96, v98, v96
	v_rcp_f32_e32 v97, v97
	s_nop 0
	v_add_f32_e32 v97, v97, v97
	v_sub_f32_e32 v97, 1.0, v97
	v_mul_f32_e32 v98, 0.5, v99
	v_add_f32_e32 v97, 1.0, v97
	v_mul_f32_e32 v97, v98, v97
	v_mul_f32_e32 v98, 0x3d372713, v92
	v_mul_f32_e32 v98, v92, v98
	v_fma_f32 v98, v92, v98, v92
	v_mul_f32_e32 v98, 0x3f4c422a, v98
	v_add_f32_e32 v98, v98, v98
	v_mul_f32_e32 v98, 0x3fb8aa3b, v98
	v_exp_f32_e32 v98, v98
	v_cvt_pk_bf16_f32 v103, v96, v97
	v_add_u32_e32 v96, v112, v147
	v_ashrrev_i32_e32 v97, 31, v96
	v_add_f32_e32 v98, 1.0, v98
	v_lshlrev_b64 v[96:97], 10, v[96:97]
	v_lshl_add_u64 v[96:97], s[60:61], 0, v[96:97]
	v_lshl_add_u64 v[96:97], v[96:97], 0, s[18:19]
	v_lshl_add_u64 v[96:97], v[96:97], 0, v[136:137]
	global_store_dwordx4 v[96:97], v[100:103], off
	v_mul_f32_e32 v99, 0x3d372713, v93
	v_mul_f32_e32 v99, v93, v99
	v_fma_f32 v99, v93, v99, v93
	v_mul_f32_e32 v99, 0x3f4c422a, v99
	v_add_f32_e32 v99, v99, v99
	v_mul_f32_e32 v99, 0x3fb8aa3b, v99
	v_exp_f32_e32 v99, v99
	v_rcp_f32_e32 v97, v98
	s_nop 0
	v_add_f32_e32 v97, v97, v97
	v_sub_f32_e32 v97, 1.0, v97
	v_add_f32_e32 v98, 1.0, v99
	v_mul_f32_e32 v92, 0.5, v92
	v_add_f32_e32 v97, 1.0, v97
	v_mul_f32_e32 v92, v92, v97
	v_mul_f32_e32 v99, 0x3d372713, v94
	v_mul_f32_e32 v99, v94, v99
	v_fma_f32 v99, v94, v99, v94
	v_mul_f32_e32 v99, 0x3f4c422a, v99
	v_add_f32_e32 v99, v99, v99
	v_mul_f32_e32 v99, 0x3fb8aa3b, v99
	v_exp_f32_e32 v99, v99
	v_rcp_f32_e32 v97, v98
	s_nop 0
	v_add_f32_e32 v97, v97, v97
	v_sub_f32_e32 v97, 1.0, v97
	v_add_f32_e32 v98, 1.0, v99
	v_mul_f32_e32 v93, 0.5, v93
	v_add_f32_e32 v97, 1.0, v97
	v_mul_f32_e32 v93, v93, v97
	v_cvt_pk_bf16_f32 v92, v92, v93
	v_mul_f32_e32 v99, 0x3d372713, v95
	v_mul_f32_e32 v99, v95, v99
	v_fma_f32 v99, v95, v99, v95
	v_mul_f32_e32 v99, 0x3f4c422a, v99
	v_add_f32_e32 v99, v99, v99
	v_mul_f32_e32 v99, 0x3fb8aa3b, v99
	v_exp_f32_e32 v99, v99
	v_rcp_f32_e32 v93, v98
	s_nop 0
	v_add_f32_e32 v93, v93, v93
	v_sub_f32_e32 v93, 1.0, v93
	v_add_f32_e32 v97, 1.0, v99
	v_mul_f32_e32 v94, 0.5, v94
	v_add_f32_e32 v93, 1.0, v93
	v_mul_f32_e32 v93, v94, v93
	v_mul_f32_e32 v98, 0x3d372713, v88
	v_mul_f32_e32 v98, v88, v98
	v_fma_f32 v98, v88, v98, v88
	v_mul_f32_e32 v98, 0x3f4c422a, v98
	v_add_f32_e32 v98, v98, v98
	v_mul_f32_e32 v98, 0x3fb8aa3b, v98
	v_exp_f32_e32 v98, v98
	v_rcp_f32_e32 v94, v97
	s_nop 0
	v_add_f32_e32 v94, v94, v94
	v_sub_f32_e32 v94, 1.0, v94
	v_add_f32_e32 v97, 1.0, v98
	v_mul_f32_e32 v95, 0.5, v95
	v_add_f32_e32 v94, 1.0, v94
	v_mul_f32_e32 v94, v95, v94
	v_cvt_pk_bf16_f32 v93, v93, v94
	v_mul_f32_e32 v98, 0x3d372713, v89
	v_mul_f32_e32 v98, v89, v98
	v_fma_f32 v98, v89, v98, v89
	v_mul_f32_e32 v98, 0x3f4c422a, v98
	v_add_f32_e32 v98, v98, v98
	v_mul_f32_e32 v98, 0x3fb8aa3b, v98
	v_exp_f32_e32 v98, v98
	v_rcp_f32_e32 v94, v97
	s_nop 0
	v_add_f32_e32 v94, v94, v94
	v_sub_f32_e32 v94, 1.0, v94
	v_add_f32_e32 v95, 1.0, v98
	v_mul_f32_e32 v88, 0.5, v88
	v_add_f32_e32 v94, 1.0, v94
	v_mul_f32_e32 v88, v88, v94
	v_mul_f32_e32 v97, 0x3d372713, v90
	v_mul_f32_e32 v97, v90, v97
	v_fma_f32 v97, v90, v97, v90
	v_mul_f32_e32 v97, 0x3f4c422a, v97
	v_add_f32_e32 v97, v97, v97
	v_mul_f32_e32 v97, 0x3fb8aa3b, v97
	v_exp_f32_e32 v97, v97
	v_rcp_f32_e32 v94, v95
	s_nop 0
	v_add_f32_e32 v94, v94, v94
	v_sub_f32_e32 v94, 1.0, v94
	v_add_f32_e32 v95, 1.0, v97
	v_mul_f32_e32 v89, 0.5, v89
	v_add_f32_e32 v94, 1.0, v94
	v_mul_f32_e32 v89, v89, v94
	v_cvt_pk_bf16_f32 v94, v88, v89
	v_mul_f32_e32 v97, 0x3d372713, v91
	v_mul_f32_e32 v97, v91, v97
	v_fma_f32 v97, v91, v97, v91
	v_mul_f32_e32 v97, 0x3f4c422a, v97
	v_add_f32_e32 v97, v97, v97
	v_mul_f32_e32 v97, 0x3fb8aa3b, v97
	v_exp_f32_e32 v97, v97
	v_rcp_f32_e32 v88, v95
	s_nop 0
	v_add_f32_e32 v88, v88, v88
	v_sub_f32_e32 v88, 1.0, v88
	v_add_f32_e32 v89, 1.0, v97
	v_mul_f32_e32 v90, 0.5, v90
	v_add_f32_e32 v88, 1.0, v88
	v_mul_f32_e32 v88, v90, v88
	v_rcp_f32_e32 v89, v89
	s_nop 0
	v_add_f32_e32 v89, v89, v89
	v_sub_f32_e32 v89, 1.0, v89
	v_mul_f32_e32 v90, 0.5, v91
	v_add_f32_e32 v89, 1.0, v89
	v_mul_f32_e32 v89, v90, v89
	v_cvt_pk_bf16_f32 v95, v88, v89
	v_mul_f32_e32 v89, 0x3d372713, v84
	v_mul_f32_e32 v89, v84, v89
	v_fma_f32 v89, v84, v89, v84
	v_mul_f32_e32 v89, 0x3f4c422a, v89
	v_add_f32_e32 v89, v89, v89
	v_mul_f32_e32 v89, 0x3fb8aa3b, v89
	v_exp_f32_e32 v90, v89
	v_or_b32_e32 v96, 0x200, v151
	v_add_u32_e32 v88, v96, v146
	v_ashrrev_i32_e32 v89, 31, v88
	v_add_f32_e32 v90, 1.0, v90
	v_lshlrev_b64 v[88:89], 10, v[88:89]
	v_lshl_add_u64 v[88:89], s[60:61], 0, v[88:89]
	v_lshl_add_u64 v[88:89], v[88:89], 0, s[18:19]
	v_lshl_add_u64 v[88:89], v[88:89], 0, v[136:137]
	global_store_dwordx4 v[88:89], v[92:95], off
	v_mul_f32_e32 v91, 0x3d372713, v85
	v_mul_f32_e32 v91, v85, v91
	v_fma_f32 v91, v85, v91, v85
	v_mul_f32_e32 v91, 0x3f4c422a, v91
	v_add_f32_e32 v91, v91, v91
	v_mul_f32_e32 v91, 0x3fb8aa3b, v91
	v_exp_f32_e32 v91, v91
	v_rcp_f32_e32 v88, v90
	s_nop 0
	v_add_f32_e32 v88, v88, v88
	v_sub_f32_e32 v88, 1.0, v88
	v_add_f32_e32 v89, 1.0, v91
	v_mul_f32_e32 v84, 0.5, v84
	v_add_f32_e32 v88, 1.0, v88
	v_mul_f32_e32 v84, v84, v88
	v_mul_f32_e32 v90, 0x3d372713, v86
	v_mul_f32_e32 v90, v86, v90
	v_fma_f32 v90, v86, v90, v86
	v_mul_f32_e32 v90, 0x3f4c422a, v90
	v_add_f32_e32 v90, v90, v90
	v_mul_f32_e32 v90, 0x3fb8aa3b, v90
	v_exp_f32_e32 v90, v90
	v_rcp_f32_e32 v88, v89
	s_nop 0
	v_add_f32_e32 v88, v88, v88
	v_sub_f32_e32 v88, 1.0, v88
	v_add_f32_e32 v89, 1.0, v90
	v_mul_f32_e32 v85, 0.5, v85
	v_add_f32_e32 v88, 1.0, v88
	v_mul_f32_e32 v85, v85, v88
	v_cvt_pk_bf16_f32 v84, v84, v85
	v_mul_f32_e32 v90, 0x3d372713, v87
	v_mul_f32_e32 v90, v87, v90
	v_fma_f32 v90, v87, v90, v87
	v_mul_f32_e32 v90, 0x3f4c422a, v90
	v_add_f32_e32 v90, v90, v90
	v_mul_f32_e32 v90, 0x3fb8aa3b, v90
	v_exp_f32_e32 v90, v90
	v_rcp_f32_e32 v85, v89
	s_nop 0
	v_add_f32_e32 v85, v85, v85
	v_sub_f32_e32 v85, 1.0, v85
	v_add_f32_e32 v88, 1.0, v90
	v_mul_f32_e32 v86, 0.5, v86
	v_add_f32_e32 v85, 1.0, v85
	v_mul_f32_e32 v85, v86, v85
	v_mul_f32_e32 v89, 0x3d372713, v80
	v_mul_f32_e32 v89, v80, v89
	v_fma_f32 v89, v80, v89, v80
	v_mul_f32_e32 v89, 0x3f4c422a, v89
	v_add_f32_e32 v89, v89, v89
	v_mul_f32_e32 v89, 0x3fb8aa3b, v89
	v_exp_f32_e32 v89, v89
	v_rcp_f32_e32 v86, v88
	s_nop 0
	v_add_f32_e32 v86, v86, v86
	v_sub_f32_e32 v86, 1.0, v86
	v_add_f32_e32 v88, 1.0, v89
	v_mul_f32_e32 v87, 0.5, v87
	v_add_f32_e32 v86, 1.0, v86
	v_mul_f32_e32 v86, v87, v86
	v_cvt_pk_bf16_f32 v85, v85, v86
	v_mul_f32_e32 v89, 0x3d372713, v81
	v_mul_f32_e32 v89, v81, v89
	v_fma_f32 v89, v81, v89, v81
	v_mul_f32_e32 v89, 0x3f4c422a, v89
	v_add_f32_e32 v89, v89, v89
	v_mul_f32_e32 v89, 0x3fb8aa3b, v89
	v_exp_f32_e32 v89, v89
	v_rcp_f32_e32 v86, v88
	s_nop 0
	v_add_f32_e32 v86, v86, v86
	v_sub_f32_e32 v86, 1.0, v86
	v_add_f32_e32 v87, 1.0, v89
	v_mul_f32_e32 v80, 0.5, v80
	v_add_f32_e32 v86, 1.0, v86
	v_mul_f32_e32 v80, v80, v86
	v_mul_f32_e32 v88, 0x3d372713, v82
	v_mul_f32_e32 v88, v82, v88
	v_fma_f32 v88, v82, v88, v82
	v_mul_f32_e32 v88, 0x3f4c422a, v88
	v_add_f32_e32 v88, v88, v88
	v_mul_f32_e32 v88, 0x3fb8aa3b, v88
	v_exp_f32_e32 v88, v88
	v_rcp_f32_e32 v86, v87
	s_nop 0
	v_add_f32_e32 v86, v86, v86
	v_sub_f32_e32 v86, 1.0, v86
	v_add_f32_e32 v87, 1.0, v88
	v_mul_f32_e32 v81, 0.5, v81
	v_add_f32_e32 v86, 1.0, v86
	v_mul_f32_e32 v81, v81, v86
	v_cvt_pk_bf16_f32 v86, v80, v81
	v_mul_f32_e32 v88, 0x3d372713, v83
	v_mul_f32_e32 v88, v83, v88
	v_fma_f32 v88, v83, v88, v83
	v_mul_f32_e32 v88, 0x3f4c422a, v88
	v_add_f32_e32 v88, v88, v88
	v_mul_f32_e32 v88, 0x3fb8aa3b, v88
	v_exp_f32_e32 v88, v88
	v_rcp_f32_e32 v80, v87
	s_nop 0
	v_add_f32_e32 v80, v80, v80
	v_sub_f32_e32 v80, 1.0, v80
	v_add_f32_e32 v81, 1.0, v88
	v_mul_f32_e32 v82, 0.5, v82
	v_add_f32_e32 v80, 1.0, v80
	v_mul_f32_e32 v80, v82, v80
	v_rcp_f32_e32 v81, v81
	s_nop 0
	v_add_f32_e32 v81, v81, v81
	v_sub_f32_e32 v81, 1.0, v81
	v_mul_f32_e32 v82, 0.5, v83
	v_add_f32_e32 v81, 1.0, v81
	v_mul_f32_e32 v81, v82, v81
	v_mul_f32_e32 v82, 0x3d372713, v76
	v_mul_f32_e32 v82, v76, v82
	v_fma_f32 v82, v76, v82, v76
	v_mul_f32_e32 v82, 0x3f4c422a, v82
	v_add_f32_e32 v82, v82, v82
	v_mul_f32_e32 v82, 0x3fb8aa3b, v82
	v_exp_f32_e32 v82, v82
	v_cvt_pk_bf16_f32 v87, v80, v81
	v_add_u32_e32 v80, v96, v147
	v_ashrrev_i32_e32 v81, 31, v80
	v_add_f32_e32 v82, 1.0, v82
	v_lshlrev_b64 v[80:81], 10, v[80:81]
	v_lshl_add_u64 v[80:81], s[60:61], 0, v[80:81]
	v_lshl_add_u64 v[80:81], v[80:81], 0, s[18:19]
	v_lshl_add_u64 v[80:81], v[80:81], 0, v[136:137]
	global_store_dwordx4 v[80:81], v[84:87], off
	v_mul_f32_e32 v83, 0x3d372713, v77
	v_mul_f32_e32 v83, v77, v83
	v_fma_f32 v83, v77, v83, v77
	v_mul_f32_e32 v83, 0x3f4c422a, v83
	v_add_f32_e32 v83, v83, v83
	v_mul_f32_e32 v83, 0x3fb8aa3b, v83
	v_exp_f32_e32 v83, v83
	v_rcp_f32_e32 v81, v82
	s_nop 0
	v_add_f32_e32 v81, v81, v81
	v_sub_f32_e32 v81, 1.0, v81
	v_add_f32_e32 v82, 1.0, v83
	v_mul_f32_e32 v76, 0.5, v76
	v_add_f32_e32 v81, 1.0, v81
	v_mul_f32_e32 v76, v76, v81
	v_mul_f32_e32 v83, 0x3d372713, v78
	v_mul_f32_e32 v83, v78, v83
	v_fma_f32 v83, v78, v83, v78
	v_mul_f32_e32 v83, 0x3f4c422a, v83
	v_add_f32_e32 v83, v83, v83
	v_mul_f32_e32 v83, 0x3fb8aa3b, v83
	v_exp_f32_e32 v83, v83
	v_rcp_f32_e32 v81, v82
	s_nop 0
	v_add_f32_e32 v81, v81, v81
	v_sub_f32_e32 v81, 1.0, v81
	v_add_f32_e32 v82, 1.0, v83
	v_mul_f32_e32 v77, 0.5, v77
	v_add_f32_e32 v81, 1.0, v81
	v_mul_f32_e32 v77, v77, v81
	v_cvt_pk_bf16_f32 v76, v76, v77
	v_mul_f32_e32 v83, 0x3d372713, v79
	v_mul_f32_e32 v83, v79, v83
	v_fma_f32 v83, v79, v83, v79
	v_mul_f32_e32 v83, 0x3f4c422a, v83
	v_add_f32_e32 v83, v83, v83
	v_mul_f32_e32 v83, 0x3fb8aa3b, v83
	v_exp_f32_e32 v83, v83
	v_rcp_f32_e32 v77, v82
	s_nop 0
	v_add_f32_e32 v77, v77, v77
	v_sub_f32_e32 v77, 1.0, v77
	v_add_f32_e32 v81, 1.0, v83
	v_mul_f32_e32 v78, 0.5, v78
	v_add_f32_e32 v77, 1.0, v77
	v_mul_f32_e32 v77, v78, v77
	v_mul_f32_e32 v82, 0x3d372713, v72
	v_mul_f32_e32 v82, v72, v82
	v_fma_f32 v82, v72, v82, v72
	v_mul_f32_e32 v82, 0x3f4c422a, v82
	v_add_f32_e32 v82, v82, v82
	v_mul_f32_e32 v82, 0x3fb8aa3b, v82
	v_exp_f32_e32 v82, v82
	v_rcp_f32_e32 v78, v81
	s_nop 0
	v_add_f32_e32 v78, v78, v78
	v_sub_f32_e32 v78, 1.0, v78
	v_add_f32_e32 v81, 1.0, v82
	v_mul_f32_e32 v79, 0.5, v79
	v_add_f32_e32 v78, 1.0, v78
	v_mul_f32_e32 v78, v79, v78
	v_cvt_pk_bf16_f32 v77, v77, v78
	v_mul_f32_e32 v82, 0x3d372713, v73
	v_mul_f32_e32 v82, v73, v82
	v_fma_f32 v82, v73, v82, v73
	v_mul_f32_e32 v82, 0x3f4c422a, v82
	v_add_f32_e32 v82, v82, v82
	v_mul_f32_e32 v82, 0x3fb8aa3b, v82
	v_exp_f32_e32 v82, v82
	v_rcp_f32_e32 v78, v81
	s_nop 0
	v_add_f32_e32 v78, v78, v78
	v_sub_f32_e32 v78, 1.0, v78
	v_add_f32_e32 v79, 1.0, v82
	v_mul_f32_e32 v72, 0.5, v72
	v_add_f32_e32 v78, 1.0, v78
	v_mul_f32_e32 v72, v72, v78
	v_mul_f32_e32 v81, 0x3d372713, v74
	v_mul_f32_e32 v81, v74, v81
	v_fma_f32 v81, v74, v81, v74
	v_mul_f32_e32 v81, 0x3f4c422a, v81
	v_add_f32_e32 v81, v81, v81
	v_mul_f32_e32 v81, 0x3fb8aa3b, v81
	v_exp_f32_e32 v81, v81
	v_rcp_f32_e32 v78, v79
	s_nop 0
	v_add_f32_e32 v78, v78, v78
	v_sub_f32_e32 v78, 1.0, v78
	v_add_f32_e32 v79, 1.0, v81
	v_mul_f32_e32 v73, 0.5, v73
	v_add_f32_e32 v78, 1.0, v78
	v_mul_f32_e32 v73, v73, v78
	v_cvt_pk_bf16_f32 v78, v72, v73
	v_mul_f32_e32 v81, 0x3d372713, v75
	v_mul_f32_e32 v81, v75, v81
	v_fma_f32 v81, v75, v81, v75
	v_mul_f32_e32 v81, 0x3f4c422a, v81
	v_add_f32_e32 v81, v81, v81
	v_mul_f32_e32 v81, 0x3fb8aa3b, v81
	v_exp_f32_e32 v81, v81
	v_rcp_f32_e32 v72, v79
	s_nop 0
	v_add_f32_e32 v72, v72, v72
	v_sub_f32_e32 v72, 1.0, v72
	v_add_f32_e32 v73, 1.0, v81
	v_mul_f32_e32 v74, 0.5, v74
	v_add_f32_e32 v72, 1.0, v72
	v_mul_f32_e32 v72, v74, v72
	v_rcp_f32_e32 v73, v73
	s_nop 0
	v_add_f32_e32 v73, v73, v73
	v_sub_f32_e32 v73, 1.0, v73
	v_mul_f32_e32 v74, 0.5, v75
	v_add_f32_e32 v73, 1.0, v73
	v_mul_f32_e32 v73, v74, v73
	v_cvt_pk_bf16_f32 v79, v72, v73
	v_mul_f32_e32 v73, 0x3d372713, v68
	v_mul_f32_e32 v73, v68, v73
	v_fma_f32 v73, v68, v73, v68
	v_mul_f32_e32 v73, 0x3f4c422a, v73
	v_add_f32_e32 v73, v73, v73
	v_mul_f32_e32 v73, 0x3fb8aa3b, v73
	v_exp_f32_e32 v74, v73
	v_or_b32_e32 v80, 0x300, v151
	v_add_u32_e32 v72, v80, v146
	v_ashrrev_i32_e32 v73, 31, v72
	v_add_f32_e32 v74, 1.0, v74
	v_lshlrev_b64 v[72:73], 10, v[72:73]
	v_lshl_add_u64 v[72:73], s[60:61], 0, v[72:73]
	v_lshl_add_u64 v[72:73], v[72:73], 0, s[18:19]
	v_lshl_add_u64 v[72:73], v[72:73], 0, v[136:137]
	global_store_dwordx4 v[72:73], v[76:79], off
	v_mul_f32_e32 v75, 0x3d372713, v69
	v_mul_f32_e32 v75, v69, v75
	v_fma_f32 v75, v69, v75, v69
	v_mul_f32_e32 v75, 0x3f4c422a, v75
	v_add_f32_e32 v75, v75, v75
	v_mul_f32_e32 v75, 0x3fb8aa3b, v75
	v_exp_f32_e32 v75, v75
	v_rcp_f32_e32 v72, v74
	s_nop 0
	v_add_f32_e32 v72, v72, v72
	v_sub_f32_e32 v72, 1.0, v72
	v_add_f32_e32 v73, 1.0, v75
	v_mul_f32_e32 v68, 0.5, v68
	v_add_f32_e32 v72, 1.0, v72
	v_mul_f32_e32 v68, v68, v72
	v_mul_f32_e32 v74, 0x3d372713, v70
	v_mul_f32_e32 v74, v70, v74
	v_fma_f32 v74, v70, v74, v70
	v_mul_f32_e32 v74, 0x3f4c422a, v74
	v_add_f32_e32 v74, v74, v74
	v_mul_f32_e32 v74, 0x3fb8aa3b, v74
	v_exp_f32_e32 v74, v74
	v_rcp_f32_e32 v72, v73
	s_nop 0
	v_add_f32_e32 v72, v72, v72
	v_sub_f32_e32 v72, 1.0, v72
	v_add_f32_e32 v73, 1.0, v74
	v_mul_f32_e32 v69, 0.5, v69
	v_add_f32_e32 v72, 1.0, v72
	v_mul_f32_e32 v69, v69, v72
	v_cvt_pk_bf16_f32 v68, v68, v69
	v_mul_f32_e32 v74, 0x3d372713, v71
	v_mul_f32_e32 v74, v71, v74
	v_fma_f32 v74, v71, v74, v71
	v_mul_f32_e32 v74, 0x3f4c422a, v74
	v_add_f32_e32 v74, v74, v74
	v_mul_f32_e32 v74, 0x3fb8aa3b, v74
	v_exp_f32_e32 v74, v74
	v_rcp_f32_e32 v69, v73
	s_nop 0
	v_add_f32_e32 v69, v69, v69
	v_sub_f32_e32 v69, 1.0, v69
	v_add_f32_e32 v72, 1.0, v74
	v_mul_f32_e32 v70, 0.5, v70
	v_add_f32_e32 v69, 1.0, v69
	v_mul_f32_e32 v69, v70, v69
	v_mul_f32_e32 v73, 0x3d372713, v64
	v_mul_f32_e32 v73, v64, v73
	v_fma_f32 v73, v64, v73, v64
	v_mul_f32_e32 v73, 0x3f4c422a, v73
	v_add_f32_e32 v73, v73, v73
	v_mul_f32_e32 v73, 0x3fb8aa3b, v73
	v_exp_f32_e32 v73, v73
	v_rcp_f32_e32 v70, v72
	s_nop 0
	v_add_f32_e32 v70, v70, v70
	v_sub_f32_e32 v70, 1.0, v70
	v_add_f32_e32 v72, 1.0, v73
	v_mul_f32_e32 v71, 0.5, v71
	v_add_f32_e32 v70, 1.0, v70
	v_mul_f32_e32 v70, v71, v70
	v_cvt_pk_bf16_f32 v69, v69, v70
	v_mul_f32_e32 v73, 0x3d372713, v65
	v_mul_f32_e32 v73, v65, v73
	v_fma_f32 v73, v65, v73, v65
	v_mul_f32_e32 v73, 0x3f4c422a, v73
	v_add_f32_e32 v73, v73, v73
	v_mul_f32_e32 v73, 0x3fb8aa3b, v73
	v_exp_f32_e32 v73, v73
	v_rcp_f32_e32 v70, v72
	s_nop 0
	v_add_f32_e32 v70, v70, v70
	v_sub_f32_e32 v70, 1.0, v70
	v_add_f32_e32 v71, 1.0, v73
	v_mul_f32_e32 v64, 0.5, v64
	v_add_f32_e32 v70, 1.0, v70
	v_mul_f32_e32 v64, v64, v70
	v_mul_f32_e32 v72, 0x3d372713, v66
	v_mul_f32_e32 v72, v66, v72
	v_fma_f32 v72, v66, v72, v66
	v_mul_f32_e32 v72, 0x3f4c422a, v72
	v_add_f32_e32 v72, v72, v72
	v_mul_f32_e32 v72, 0x3fb8aa3b, v72
	v_exp_f32_e32 v72, v72
	v_rcp_f32_e32 v70, v71
	s_nop 0
	v_add_f32_e32 v70, v70, v70
	v_sub_f32_e32 v70, 1.0, v70
	v_add_f32_e32 v71, 1.0, v72
	v_mul_f32_e32 v65, 0.5, v65
	v_add_f32_e32 v70, 1.0, v70
	v_mul_f32_e32 v65, v65, v70
	v_cvt_pk_bf16_f32 v70, v64, v65
	v_mul_f32_e32 v72, 0x3d372713, v67
	v_mul_f32_e32 v72, v67, v72
	v_fma_f32 v72, v67, v72, v67
	v_mul_f32_e32 v72, 0x3f4c422a, v72
	v_add_f32_e32 v72, v72, v72
	v_mul_f32_e32 v72, 0x3fb8aa3b, v72
	v_exp_f32_e32 v72, v72
	v_rcp_f32_e32 v64, v71
	s_nop 0
	v_add_f32_e32 v64, v64, v64
	v_sub_f32_e32 v64, 1.0, v64
	v_add_f32_e32 v65, 1.0, v72
	v_mul_f32_e32 v66, 0.5, v66
	v_add_f32_e32 v64, 1.0, v64
	v_mul_f32_e32 v64, v66, v64
	v_rcp_f32_e32 v65, v65
	s_nop 0
	v_add_f32_e32 v65, v65, v65
	v_sub_f32_e32 v65, 1.0, v65
	v_mul_f32_e32 v66, 0.5, v67
	v_add_f32_e32 v65, 1.0, v65
	v_mul_f32_e32 v65, v66, v65
	v_mul_f32_e32 v66, 0x3d372713, v60
	v_mul_f32_e32 v66, v60, v66
	v_fma_f32 v66, v60, v66, v60
	v_mul_f32_e32 v66, 0x3f4c422a, v66
	v_add_f32_e32 v66, v66, v66
	v_mul_f32_e32 v66, 0x3fb8aa3b, v66
	v_exp_f32_e32 v66, v66
	v_cvt_pk_bf16_f32 v71, v64, v65
	v_add_u32_e32 v64, v80, v147
	v_ashrrev_i32_e32 v65, 31, v64
	v_add_f32_e32 v66, 1.0, v66
	v_lshlrev_b64 v[64:65], 10, v[64:65]
	v_lshl_add_u64 v[64:65], s[60:61], 0, v[64:65]
	v_lshl_add_u64 v[64:65], v[64:65], 0, s[18:19]
	v_lshl_add_u64 v[64:65], v[64:65], 0, v[136:137]
	global_store_dwordx4 v[64:65], v[68:71], off
	v_mul_f32_e32 v67, 0x3d372713, v61
	v_mul_f32_e32 v67, v61, v67
	v_fma_f32 v67, v61, v67, v61
	v_mul_f32_e32 v67, 0x3f4c422a, v67
	v_add_f32_e32 v67, v67, v67
	v_mul_f32_e32 v67, 0x3fb8aa3b, v67
	v_exp_f32_e32 v67, v67
	v_rcp_f32_e32 v65, v66
	s_nop 0
	v_add_f32_e32 v65, v65, v65
	v_sub_f32_e32 v65, 1.0, v65
	v_add_f32_e32 v66, 1.0, v67
	v_mul_f32_e32 v60, 0.5, v60
	v_add_f32_e32 v65, 1.0, v65
	v_mul_f32_e32 v60, v60, v65
	v_mul_f32_e32 v67, 0x3d372713, v62
	v_mul_f32_e32 v67, v62, v67
	v_fma_f32 v67, v62, v67, v62
	v_mul_f32_e32 v67, 0x3f4c422a, v67
	v_add_f32_e32 v67, v67, v67
	v_mul_f32_e32 v67, 0x3fb8aa3b, v67
	v_exp_f32_e32 v67, v67
	v_rcp_f32_e32 v65, v66
	s_nop 0
	v_add_f32_e32 v65, v65, v65
	v_sub_f32_e32 v65, 1.0, v65
	v_add_f32_e32 v66, 1.0, v67
	v_mul_f32_e32 v61, 0.5, v61
	v_add_f32_e32 v65, 1.0, v65
	v_mul_f32_e32 v61, v61, v65
	v_cvt_pk_bf16_f32 v60, v60, v61
	v_mul_f32_e32 v67, 0x3d372713, v63
	v_mul_f32_e32 v67, v63, v67
	v_fma_f32 v67, v63, v67, v63
	v_mul_f32_e32 v67, 0x3f4c422a, v67
	v_add_f32_e32 v67, v67, v67
	v_mul_f32_e32 v67, 0x3fb8aa3b, v67
	v_exp_f32_e32 v67, v67
	v_rcp_f32_e32 v61, v66
	s_nop 0
	v_add_f32_e32 v61, v61, v61
	v_sub_f32_e32 v61, 1.0, v61
	v_add_f32_e32 v65, 1.0, v67
	v_mul_f32_e32 v62, 0.5, v62
	v_add_f32_e32 v61, 1.0, v61
	v_mul_f32_e32 v61, v62, v61
	v_mul_f32_e32 v66, 0x3d372713, v56
	v_mul_f32_e32 v66, v56, v66
	v_fma_f32 v66, v56, v66, v56
	v_mul_f32_e32 v66, 0x3f4c422a, v66
	v_add_f32_e32 v66, v66, v66
	v_mul_f32_e32 v66, 0x3fb8aa3b, v66
	v_exp_f32_e32 v66, v66
	v_rcp_f32_e32 v62, v65
	s_nop 0
	v_add_f32_e32 v62, v62, v62
	v_sub_f32_e32 v62, 1.0, v62
	v_add_f32_e32 v65, 1.0, v66
	v_mul_f32_e32 v63, 0.5, v63
	v_add_f32_e32 v62, 1.0, v62
	v_mul_f32_e32 v62, v63, v62
	v_cvt_pk_bf16_f32 v61, v61, v62
	v_mul_f32_e32 v66, 0x3d372713, v57
	v_mul_f32_e32 v66, v57, v66
	v_fma_f32 v66, v57, v66, v57
	v_mul_f32_e32 v66, 0x3f4c422a, v66
	v_add_f32_e32 v66, v66, v66
	v_mul_f32_e32 v66, 0x3fb8aa3b, v66
	v_exp_f32_e32 v66, v66
	v_rcp_f32_e32 v62, v65
	s_nop 0
	v_add_f32_e32 v62, v62, v62
	v_sub_f32_e32 v62, 1.0, v62
	v_add_f32_e32 v63, 1.0, v66
	v_mul_f32_e32 v56, 0.5, v56
	v_add_f32_e32 v62, 1.0, v62
	v_mul_f32_e32 v56, v56, v62
	v_mul_f32_e32 v65, 0x3d372713, v58
	v_mul_f32_e32 v65, v58, v65
	v_fma_f32 v65, v58, v65, v58
	v_mul_f32_e32 v65, 0x3f4c422a, v65
	v_add_f32_e32 v65, v65, v65
	v_mul_f32_e32 v65, 0x3fb8aa3b, v65
	v_exp_f32_e32 v65, v65
	v_rcp_f32_e32 v62, v63
	s_nop 0
	v_add_f32_e32 v62, v62, v62
	v_sub_f32_e32 v62, 1.0, v62
	v_add_f32_e32 v63, 1.0, v65
	v_mul_f32_e32 v57, 0.5, v57
	v_add_f32_e32 v62, 1.0, v62
	v_mul_f32_e32 v57, v57, v62
	v_cvt_pk_bf16_f32 v62, v56, v57
	v_mul_f32_e32 v65, 0x3d372713, v59
	v_mul_f32_e32 v65, v59, v65
	v_fma_f32 v65, v59, v65, v59
	v_mul_f32_e32 v65, 0x3f4c422a, v65
	v_add_f32_e32 v65, v65, v65
	v_mul_f32_e32 v65, 0x3fb8aa3b, v65
	v_exp_f32_e32 v65, v65
	v_rcp_f32_e32 v56, v63
	s_nop 0
	v_add_f32_e32 v56, v56, v56
	v_sub_f32_e32 v56, 1.0, v56
	v_add_f32_e32 v57, 1.0, v65
	v_mul_f32_e32 v58, 0.5, v58
	v_add_f32_e32 v56, 1.0, v56
	v_mul_f32_e32 v56, v58, v56
	v_rcp_f32_e32 v57, v57
	s_nop 0
	v_add_f32_e32 v57, v57, v57
	v_sub_f32_e32 v57, 1.0, v57
	v_mul_f32_e32 v58, 0.5, v59
	v_add_f32_e32 v57, 1.0, v57
	v_mul_f32_e32 v57, v58, v57
	v_cvt_pk_bf16_f32 v63, v56, v57
	v_mul_f32_e32 v57, 0x3d372713, v52
	v_mul_f32_e32 v57, v52, v57
	v_fma_f32 v57, v52, v57, v52
	v_mul_f32_e32 v57, 0x3f4c422a, v57
	v_add_f32_e32 v57, v57, v57
	v_mul_f32_e32 v57, 0x3fb8aa3b, v57
	v_exp_f32_e32 v58, v57
	v_add_u32_e32 v64, 0x800, v151
	v_add_u32_e32 v56, v64, v146
	v_ashrrev_i32_e32 v57, 31, v56
	v_add_f32_e32 v58, 1.0, v58
	v_lshlrev_b64 v[56:57], 10, v[56:57]
	v_lshl_add_u64 v[56:57], s[60:61], 0, v[56:57]
	v_lshl_add_u64 v[56:57], v[56:57], 0, s[18:19]
	v_lshl_add_u64 v[56:57], v[56:57], 0, v[136:137]
	global_store_dwordx4 v[56:57], v[60:63], off
	v_mul_f32_e32 v59, 0x3d372713, v53
	v_mul_f32_e32 v59, v53, v59
	v_fma_f32 v59, v53, v59, v53
	v_mul_f32_e32 v59, 0x3f4c422a, v59
	v_add_f32_e32 v59, v59, v59
	v_mul_f32_e32 v59, 0x3fb8aa3b, v59
	v_exp_f32_e32 v59, v59
	v_rcp_f32_e32 v56, v58
	s_nop 0
	v_add_f32_e32 v56, v56, v56
	v_sub_f32_e32 v56, 1.0, v56
	v_add_f32_e32 v57, 1.0, v59
	v_mul_f32_e32 v52, 0.5, v52
	v_add_f32_e32 v56, 1.0, v56
	v_mul_f32_e32 v52, v52, v56
	v_mul_f32_e32 v58, 0x3d372713, v54
	v_mul_f32_e32 v58, v54, v58
	v_fma_f32 v58, v54, v58, v54
	v_mul_f32_e32 v58, 0x3f4c422a, v58
	v_add_f32_e32 v58, v58, v58
	v_mul_f32_e32 v58, 0x3fb8aa3b, v58
	v_exp_f32_e32 v58, v58
	v_rcp_f32_e32 v56, v57
	s_nop 0
	v_add_f32_e32 v56, v56, v56
	v_sub_f32_e32 v56, 1.0, v56
	v_add_f32_e32 v57, 1.0, v58
	v_mul_f32_e32 v53, 0.5, v53
	v_add_f32_e32 v56, 1.0, v56
	v_mul_f32_e32 v53, v53, v56
	v_cvt_pk_bf16_f32 v52, v52, v53
	v_mul_f32_e32 v58, 0x3d372713, v55
	v_mul_f32_e32 v58, v55, v58
	v_fma_f32 v58, v55, v58, v55
	v_mul_f32_e32 v58, 0x3f4c422a, v58
	v_add_f32_e32 v58, v58, v58
	v_mul_f32_e32 v58, 0x3fb8aa3b, v58
	v_exp_f32_e32 v58, v58
	v_rcp_f32_e32 v53, v57
	s_nop 0
	v_add_f32_e32 v53, v53, v53
	v_sub_f32_e32 v53, 1.0, v53
	v_add_f32_e32 v56, 1.0, v58
	v_mul_f32_e32 v54, 0.5, v54
	v_add_f32_e32 v53, 1.0, v53
	v_mul_f32_e32 v53, v54, v53
	v_mul_f32_e32 v57, 0x3d372713, v48
	v_mul_f32_e32 v57, v48, v57
	v_fma_f32 v57, v48, v57, v48
	v_mul_f32_e32 v57, 0x3f4c422a, v57
	v_add_f32_e32 v57, v57, v57
	v_mul_f32_e32 v57, 0x3fb8aa3b, v57
	v_exp_f32_e32 v57, v57
	v_rcp_f32_e32 v54, v56
	s_nop 0
	v_add_f32_e32 v54, v54, v54
	v_sub_f32_e32 v54, 1.0, v54
	v_add_f32_e32 v56, 1.0, v57
	v_mul_f32_e32 v55, 0.5, v55
	v_add_f32_e32 v54, 1.0, v54
	v_mul_f32_e32 v54, v55, v54
	v_cvt_pk_bf16_f32 v53, v53, v54
	v_mul_f32_e32 v57, 0x3d372713, v49
	v_mul_f32_e32 v57, v49, v57
	v_fma_f32 v57, v49, v57, v49
	v_mul_f32_e32 v57, 0x3f4c422a, v57
	v_add_f32_e32 v57, v57, v57
	v_mul_f32_e32 v57, 0x3fb8aa3b, v57
	v_exp_f32_e32 v57, v57
	v_rcp_f32_e32 v54, v56
	s_nop 0
	v_add_f32_e32 v54, v54, v54
	v_sub_f32_e32 v54, 1.0, v54
	v_add_f32_e32 v55, 1.0, v57
	v_mul_f32_e32 v48, 0.5, v48
	v_add_f32_e32 v54, 1.0, v54
	v_mul_f32_e32 v48, v48, v54
	v_mul_f32_e32 v56, 0x3d372713, v50
	v_mul_f32_e32 v56, v50, v56
	v_fma_f32 v56, v50, v56, v50
	v_mul_f32_e32 v56, 0x3f4c422a, v56
	v_add_f32_e32 v56, v56, v56
	v_mul_f32_e32 v56, 0x3fb8aa3b, v56
	v_exp_f32_e32 v56, v56
	v_rcp_f32_e32 v54, v55
	s_nop 0
	v_add_f32_e32 v54, v54, v54
	v_sub_f32_e32 v54, 1.0, v54
	v_add_f32_e32 v55, 1.0, v56
	v_mul_f32_e32 v49, 0.5, v49
	v_add_f32_e32 v54, 1.0, v54
	v_mul_f32_e32 v49, v49, v54
	v_cvt_pk_bf16_f32 v54, v48, v49
	v_mul_f32_e32 v56, 0x3d372713, v51
	v_mul_f32_e32 v56, v51, v56
	v_fma_f32 v56, v51, v56, v51
	v_mul_f32_e32 v56, 0x3f4c422a, v56
	v_add_f32_e32 v56, v56, v56
	v_mul_f32_e32 v56, 0x3fb8aa3b, v56
	v_exp_f32_e32 v56, v56
	v_rcp_f32_e32 v48, v55
	s_nop 0
	v_add_f32_e32 v48, v48, v48
	v_sub_f32_e32 v48, 1.0, v48
	v_add_f32_e32 v49, 1.0, v56
	v_mul_f32_e32 v50, 0.5, v50
	v_add_f32_e32 v48, 1.0, v48
	v_mul_f32_e32 v48, v50, v48
	v_rcp_f32_e32 v49, v49
	s_nop 0
	v_add_f32_e32 v49, v49, v49
	v_sub_f32_e32 v49, 1.0, v49
	v_mul_f32_e32 v50, 0.5, v51
	v_add_f32_e32 v49, 1.0, v49
	v_mul_f32_e32 v49, v50, v49
	v_mul_f32_e32 v50, 0x3d372713, v44
	v_mul_f32_e32 v50, v44, v50
	v_fma_f32 v50, v44, v50, v44
	v_mul_f32_e32 v50, 0x3f4c422a, v50
	v_add_f32_e32 v50, v50, v50
	v_mul_f32_e32 v50, 0x3fb8aa3b, v50
	v_exp_f32_e32 v50, v50
	v_cvt_pk_bf16_f32 v55, v48, v49
	v_add_u32_e32 v48, v64, v147
	v_ashrrev_i32_e32 v49, 31, v48
	v_add_f32_e32 v50, 1.0, v50
	v_lshlrev_b64 v[48:49], 10, v[48:49]
	v_lshl_add_u64 v[48:49], s[60:61], 0, v[48:49]
	v_lshl_add_u64 v[48:49], v[48:49], 0, s[18:19]
	v_lshl_add_u64 v[48:49], v[48:49], 0, v[136:137]
	global_store_dwordx4 v[48:49], v[52:55], off
	v_mul_f32_e32 v51, 0x3d372713, v45
	v_mul_f32_e32 v51, v45, v51
	v_fma_f32 v51, v45, v51, v45
	v_mul_f32_e32 v51, 0x3f4c422a, v51
	v_add_f32_e32 v51, v51, v51
	v_mul_f32_e32 v51, 0x3fb8aa3b, v51
	v_exp_f32_e32 v51, v51
	v_rcp_f32_e32 v49, v50
	s_nop 0
	v_add_f32_e32 v49, v49, v49
	v_sub_f32_e32 v49, 1.0, v49
	v_add_f32_e32 v50, 1.0, v51
	v_mul_f32_e32 v44, 0.5, v44
	v_add_f32_e32 v49, 1.0, v49
	v_mul_f32_e32 v44, v44, v49
	v_mul_f32_e32 v51, 0x3d372713, v46
	v_mul_f32_e32 v51, v46, v51
	v_fma_f32 v51, v46, v51, v46
	v_mul_f32_e32 v51, 0x3f4c422a, v51
	v_add_f32_e32 v51, v51, v51
	v_mul_f32_e32 v51, 0x3fb8aa3b, v51
	v_exp_f32_e32 v51, v51
	v_rcp_f32_e32 v49, v50
	s_nop 0
	v_add_f32_e32 v49, v49, v49
	v_sub_f32_e32 v49, 1.0, v49
	v_add_f32_e32 v50, 1.0, v51
	v_mul_f32_e32 v45, 0.5, v45
	v_add_f32_e32 v49, 1.0, v49
	v_mul_f32_e32 v45, v45, v49
	v_cvt_pk_bf16_f32 v44, v44, v45
	v_mul_f32_e32 v51, 0x3d372713, v47
	v_mul_f32_e32 v51, v47, v51
	v_fma_f32 v51, v47, v51, v47
	v_mul_f32_e32 v51, 0x3f4c422a, v51
	v_add_f32_e32 v51, v51, v51
	v_mul_f32_e32 v51, 0x3fb8aa3b, v51
	v_exp_f32_e32 v51, v51
	v_rcp_f32_e32 v45, v50
	s_nop 0
	v_add_f32_e32 v45, v45, v45
	v_sub_f32_e32 v45, 1.0, v45
	v_add_f32_e32 v49, 1.0, v51
	v_mul_f32_e32 v46, 0.5, v46
	v_add_f32_e32 v45, 1.0, v45
	v_mul_f32_e32 v45, v46, v45
	v_mul_f32_e32 v50, 0x3d372713, v40
	v_mul_f32_e32 v50, v40, v50
	v_fma_f32 v50, v40, v50, v40
	v_mul_f32_e32 v50, 0x3f4c422a, v50
	v_add_f32_e32 v50, v50, v50
	v_mul_f32_e32 v50, 0x3fb8aa3b, v50
	v_exp_f32_e32 v50, v50
	v_rcp_f32_e32 v46, v49
	s_nop 0
	v_add_f32_e32 v46, v46, v46
	v_sub_f32_e32 v46, 1.0, v46
	v_add_f32_e32 v49, 1.0, v50
	v_mul_f32_e32 v47, 0.5, v47
	v_add_f32_e32 v46, 1.0, v46
	v_mul_f32_e32 v46, v47, v46
	v_cvt_pk_bf16_f32 v45, v45, v46
	v_mul_f32_e32 v50, 0x3d372713, v41
	v_mul_f32_e32 v50, v41, v50
	v_fma_f32 v50, v41, v50, v41
	v_mul_f32_e32 v50, 0x3f4c422a, v50
	v_add_f32_e32 v50, v50, v50
	v_mul_f32_e32 v50, 0x3fb8aa3b, v50
	v_exp_f32_e32 v50, v50
	v_rcp_f32_e32 v46, v49
	s_nop 0
	v_add_f32_e32 v46, v46, v46
	v_sub_f32_e32 v46, 1.0, v46
	v_add_f32_e32 v47, 1.0, v50
	v_mul_f32_e32 v40, 0.5, v40
	v_add_f32_e32 v46, 1.0, v46
	v_mul_f32_e32 v40, v40, v46
	v_mul_f32_e32 v49, 0x3d372713, v42
	v_mul_f32_e32 v49, v42, v49
	v_fma_f32 v49, v42, v49, v42
	v_mul_f32_e32 v49, 0x3f4c422a, v49
	v_add_f32_e32 v49, v49, v49
	v_mul_f32_e32 v49, 0x3fb8aa3b, v49
	v_exp_f32_e32 v49, v49
	v_rcp_f32_e32 v46, v47
	s_nop 0
	v_add_f32_e32 v46, v46, v46
	v_sub_f32_e32 v46, 1.0, v46
	v_add_f32_e32 v47, 1.0, v49
	v_mul_f32_e32 v41, 0.5, v41
	v_add_f32_e32 v46, 1.0, v46
	v_mul_f32_e32 v41, v41, v46
	v_cvt_pk_bf16_f32 v46, v40, v41
	v_mul_f32_e32 v49, 0x3d372713, v43
	v_mul_f32_e32 v49, v43, v49
	v_fma_f32 v49, v43, v49, v43
	v_mul_f32_e32 v49, 0x3f4c422a, v49
	v_add_f32_e32 v49, v49, v49
	v_mul_f32_e32 v49, 0x3fb8aa3b, v49
	v_exp_f32_e32 v49, v49
	v_rcp_f32_e32 v40, v47
	s_nop 0
	v_add_f32_e32 v40, v40, v40
	v_sub_f32_e32 v40, 1.0, v40
	v_add_f32_e32 v41, 1.0, v49
	v_mul_f32_e32 v42, 0.5, v42
	v_add_f32_e32 v40, 1.0, v40
	v_mul_f32_e32 v40, v42, v40
	v_rcp_f32_e32 v41, v41
	s_nop 0
	v_add_f32_e32 v41, v41, v41
	v_sub_f32_e32 v41, 1.0, v41
	v_mul_f32_e32 v42, 0.5, v43
	v_add_f32_e32 v41, 1.0, v41
	v_mul_f32_e32 v41, v42, v41
	v_cvt_pk_bf16_f32 v47, v40, v41
	v_mul_f32_e32 v41, 0x3d372713, v36
	v_mul_f32_e32 v41, v36, v41
	v_fma_f32 v41, v36, v41, v36
	v_mul_f32_e32 v41, 0x3f4c422a, v41
	v_add_f32_e32 v41, v41, v41
	v_mul_f32_e32 v41, 0x3fb8aa3b, v41
	v_exp_f32_e32 v42, v41
	v_or_b32_e32 v48, 0x100, v64
	v_add_u32_e32 v40, v48, v146
	v_ashrrev_i32_e32 v41, 31, v40
	v_add_f32_e32 v42, 1.0, v42
	v_lshlrev_b64 v[40:41], 10, v[40:41]
	v_lshl_add_u64 v[40:41], s[60:61], 0, v[40:41]
	v_lshl_add_u64 v[40:41], v[40:41], 0, s[18:19]
	v_lshl_add_u64 v[40:41], v[40:41], 0, v[136:137]
	global_store_dwordx4 v[40:41], v[44:47], off
	v_mul_f32_e32 v43, 0x3d372713, v37
	v_mul_f32_e32 v43, v37, v43
	v_fma_f32 v43, v37, v43, v37
	v_mul_f32_e32 v43, 0x3f4c422a, v43
	v_add_f32_e32 v43, v43, v43
	v_mul_f32_e32 v43, 0x3fb8aa3b, v43
	v_exp_f32_e32 v43, v43
	v_rcp_f32_e32 v40, v42
	s_nop 0
	v_add_f32_e32 v40, v40, v40
	v_sub_f32_e32 v40, 1.0, v40
	v_add_f32_e32 v41, 1.0, v43
	v_mul_f32_e32 v36, 0.5, v36
	v_add_f32_e32 v40, 1.0, v40
	v_mul_f32_e32 v36, v36, v40
	v_mul_f32_e32 v42, 0x3d372713, v38
	v_mul_f32_e32 v42, v38, v42
	v_fma_f32 v42, v38, v42, v38
	v_mul_f32_e32 v42, 0x3f4c422a, v42
	v_add_f32_e32 v42, v42, v42
	v_mul_f32_e32 v42, 0x3fb8aa3b, v42
	v_exp_f32_e32 v42, v42
	v_rcp_f32_e32 v40, v41
	s_nop 0
	v_add_f32_e32 v40, v40, v40
	v_sub_f32_e32 v40, 1.0, v40
	v_add_f32_e32 v41, 1.0, v42
	v_mul_f32_e32 v37, 0.5, v37
	v_add_f32_e32 v40, 1.0, v40
	v_mul_f32_e32 v37, v37, v40
	v_cvt_pk_bf16_f32 v36, v36, v37
	v_mul_f32_e32 v42, 0x3d372713, v39
	v_mul_f32_e32 v42, v39, v42
	v_fma_f32 v42, v39, v42, v39
	v_mul_f32_e32 v42, 0x3f4c422a, v42
	v_add_f32_e32 v42, v42, v42
	v_mul_f32_e32 v42, 0x3fb8aa3b, v42
	v_exp_f32_e32 v42, v42
	v_rcp_f32_e32 v37, v41
	s_nop 0
	v_add_f32_e32 v37, v37, v37
	v_sub_f32_e32 v37, 1.0, v37
	v_add_f32_e32 v40, 1.0, v42
	v_mul_f32_e32 v38, 0.5, v38
	v_add_f32_e32 v37, 1.0, v37
	v_mul_f32_e32 v37, v38, v37
	v_mul_f32_e32 v41, 0x3d372713, v32
	v_mul_f32_e32 v41, v32, v41
	v_fma_f32 v41, v32, v41, v32
	v_mul_f32_e32 v41, 0x3f4c422a, v41
	v_add_f32_e32 v41, v41, v41
	v_mul_f32_e32 v41, 0x3fb8aa3b, v41
	v_exp_f32_e32 v41, v41
	v_rcp_f32_e32 v38, v40
	s_nop 0
	v_add_f32_e32 v38, v38, v38
	v_sub_f32_e32 v38, 1.0, v38
	v_add_f32_e32 v40, 1.0, v41
	v_mul_f32_e32 v39, 0.5, v39
	v_add_f32_e32 v38, 1.0, v38
	v_mul_f32_e32 v38, v39, v38
	v_cvt_pk_bf16_f32 v37, v37, v38
	v_mul_f32_e32 v41, 0x3d372713, v33
	v_mul_f32_e32 v41, v33, v41
	v_fma_f32 v41, v33, v41, v33
	v_mul_f32_e32 v41, 0x3f4c422a, v41
	v_add_f32_e32 v41, v41, v41
	v_mul_f32_e32 v41, 0x3fb8aa3b, v41
	v_exp_f32_e32 v41, v41
	v_rcp_f32_e32 v38, v40
	s_nop 0
	v_add_f32_e32 v38, v38, v38
	v_sub_f32_e32 v38, 1.0, v38
	v_add_f32_e32 v39, 1.0, v41
	v_mul_f32_e32 v32, 0.5, v32
	v_add_f32_e32 v38, 1.0, v38
	v_mul_f32_e32 v32, v32, v38
	v_mul_f32_e32 v40, 0x3d372713, v34
	v_mul_f32_e32 v40, v34, v40
	v_fma_f32 v40, v34, v40, v34
	v_mul_f32_e32 v40, 0x3f4c422a, v40
	v_add_f32_e32 v40, v40, v40
	v_mul_f32_e32 v40, 0x3fb8aa3b, v40
	v_exp_f32_e32 v40, v40
	v_rcp_f32_e32 v38, v39
	s_nop 0
	v_add_f32_e32 v38, v38, v38
	v_sub_f32_e32 v38, 1.0, v38
	v_add_f32_e32 v39, 1.0, v40
	v_mul_f32_e32 v33, 0.5, v33
	v_add_f32_e32 v38, 1.0, v38
	v_mul_f32_e32 v33, v33, v38
	v_cvt_pk_bf16_f32 v38, v32, v33
	v_mul_f32_e32 v40, 0x3d372713, v35
	v_mul_f32_e32 v40, v35, v40
	v_fma_f32 v40, v35, v40, v35
	v_mul_f32_e32 v40, 0x3f4c422a, v40
	v_add_f32_e32 v40, v40, v40
	v_mul_f32_e32 v40, 0x3fb8aa3b, v40
	v_exp_f32_e32 v40, v40
	v_rcp_f32_e32 v32, v39
	s_nop 0
	v_add_f32_e32 v32, v32, v32
	v_sub_f32_e32 v32, 1.0, v32
	v_add_f32_e32 v33, 1.0, v40
	v_mul_f32_e32 v34, 0.5, v34
	v_add_f32_e32 v32, 1.0, v32
	v_mul_f32_e32 v32, v34, v32
	v_rcp_f32_e32 v33, v33
	s_nop 0
	v_add_f32_e32 v33, v33, v33
	v_sub_f32_e32 v33, 1.0, v33
	v_mul_f32_e32 v34, 0.5, v35
	v_add_f32_e32 v33, 1.0, v33
	v_mul_f32_e32 v33, v34, v33
	v_mul_f32_e32 v34, 0x3d372713, v28
	v_mul_f32_e32 v34, v28, v34
	v_fma_f32 v34, v28, v34, v28
	v_mul_f32_e32 v34, 0x3f4c422a, v34
	v_add_f32_e32 v34, v34, v34
	v_mul_f32_e32 v34, 0x3fb8aa3b, v34
	v_exp_f32_e32 v34, v34
	v_cvt_pk_bf16_f32 v39, v32, v33
	v_add_u32_e32 v32, v48, v147
	v_ashrrev_i32_e32 v33, 31, v32
	v_add_f32_e32 v34, 1.0, v34
	v_lshlrev_b64 v[32:33], 10, v[32:33]
	v_lshl_add_u64 v[32:33], s[60:61], 0, v[32:33]
	v_lshl_add_u64 v[32:33], v[32:33], 0, s[18:19]
	v_lshl_add_u64 v[32:33], v[32:33], 0, v[136:137]
	global_store_dwordx4 v[32:33], v[36:39], off
	v_mul_f32_e32 v35, 0x3d372713, v29
	v_mul_f32_e32 v35, v29, v35
	v_fma_f32 v35, v29, v35, v29
	v_mul_f32_e32 v35, 0x3f4c422a, v35
	v_add_f32_e32 v35, v35, v35
	v_mul_f32_e32 v35, 0x3fb8aa3b, v35
	v_exp_f32_e32 v35, v35
	v_rcp_f32_e32 v33, v34
	s_nop 0
	v_add_f32_e32 v33, v33, v33
	v_sub_f32_e32 v33, 1.0, v33
	v_add_f32_e32 v34, 1.0, v35
	v_mul_f32_e32 v28, 0.5, v28
	v_add_f32_e32 v33, 1.0, v33
	v_mul_f32_e32 v28, v28, v33
	v_mul_f32_e32 v35, 0x3d372713, v30
	v_mul_f32_e32 v35, v30, v35
	v_fma_f32 v35, v30, v35, v30
	v_mul_f32_e32 v35, 0x3f4c422a, v35
	v_add_f32_e32 v35, v35, v35
	v_mul_f32_e32 v35, 0x3fb8aa3b, v35
	v_exp_f32_e32 v35, v35
	v_rcp_f32_e32 v33, v34
	s_nop 0
	v_add_f32_e32 v33, v33, v33
	v_sub_f32_e32 v33, 1.0, v33
	v_add_f32_e32 v34, 1.0, v35
	v_mul_f32_e32 v29, 0.5, v29
	v_add_f32_e32 v33, 1.0, v33
	v_mul_f32_e32 v29, v29, v33
	v_cvt_pk_bf16_f32 v28, v28, v29
	v_mul_f32_e32 v35, 0x3d372713, v31
	v_mul_f32_e32 v35, v31, v35
	v_fma_f32 v35, v31, v35, v31
	v_mul_f32_e32 v35, 0x3f4c422a, v35
	v_add_f32_e32 v35, v35, v35
	v_mul_f32_e32 v35, 0x3fb8aa3b, v35
	v_exp_f32_e32 v35, v35
	v_rcp_f32_e32 v29, v34
	s_nop 0
	v_add_f32_e32 v29, v29, v29
	v_sub_f32_e32 v29, 1.0, v29
	v_add_f32_e32 v33, 1.0, v35
	v_mul_f32_e32 v30, 0.5, v30
	v_add_f32_e32 v29, 1.0, v29
	v_mul_f32_e32 v29, v30, v29
	v_mul_f32_e32 v34, 0x3d372713, v24
	v_mul_f32_e32 v34, v24, v34
	v_fma_f32 v34, v24, v34, v24
	v_mul_f32_e32 v34, 0x3f4c422a, v34
	v_add_f32_e32 v34, v34, v34
	v_mul_f32_e32 v34, 0x3fb8aa3b, v34
	v_exp_f32_e32 v34, v34
	v_rcp_f32_e32 v30, v33
	s_nop 0
	v_add_f32_e32 v30, v30, v30
	v_sub_f32_e32 v30, 1.0, v30
	v_add_f32_e32 v33, 1.0, v34
	v_mul_f32_e32 v31, 0.5, v31
	v_add_f32_e32 v30, 1.0, v30
	v_mul_f32_e32 v30, v31, v30
	v_cvt_pk_bf16_f32 v29, v29, v30
	v_mul_f32_e32 v34, 0x3d372713, v25
	v_mul_f32_e32 v34, v25, v34
	v_fma_f32 v34, v25, v34, v25
	v_mul_f32_e32 v34, 0x3f4c422a, v34
	v_add_f32_e32 v34, v34, v34
	v_mul_f32_e32 v34, 0x3fb8aa3b, v34
	v_exp_f32_e32 v34, v34
	v_rcp_f32_e32 v30, v33
	s_nop 0
	v_add_f32_e32 v30, v30, v30
	v_sub_f32_e32 v30, 1.0, v30
	v_add_f32_e32 v31, 1.0, v34
	v_mul_f32_e32 v24, 0.5, v24
	v_add_f32_e32 v30, 1.0, v30
	v_mul_f32_e32 v24, v24, v30
	v_mul_f32_e32 v33, 0x3d372713, v26
	v_mul_f32_e32 v33, v26, v33
	v_fma_f32 v33, v26, v33, v26
	v_mul_f32_e32 v33, 0x3f4c422a, v33
	v_add_f32_e32 v33, v33, v33
	v_mul_f32_e32 v33, 0x3fb8aa3b, v33
	v_exp_f32_e32 v33, v33
	v_rcp_f32_e32 v30, v31
	s_nop 0
	v_add_f32_e32 v30, v30, v30
	v_sub_f32_e32 v30, 1.0, v30
	v_add_f32_e32 v31, 1.0, v33
	v_mul_f32_e32 v25, 0.5, v25
	v_add_f32_e32 v30, 1.0, v30
	v_mul_f32_e32 v25, v25, v30
	v_cvt_pk_bf16_f32 v30, v24, v25
	v_mul_f32_e32 v33, 0x3d372713, v27
	v_mul_f32_e32 v33, v27, v33
	v_fma_f32 v33, v27, v33, v27
	v_mul_f32_e32 v33, 0x3f4c422a, v33
	v_add_f32_e32 v33, v33, v33
	v_mul_f32_e32 v33, 0x3fb8aa3b, v33
	v_exp_f32_e32 v33, v33
	v_rcp_f32_e32 v24, v31
	s_nop 0
	v_add_f32_e32 v24, v24, v24
	v_sub_f32_e32 v24, 1.0, v24
	v_add_f32_e32 v25, 1.0, v33
	v_mul_f32_e32 v26, 0.5, v26
	v_add_f32_e32 v24, 1.0, v24
	v_mul_f32_e32 v24, v26, v24
	v_rcp_f32_e32 v25, v25
	s_nop 0
	v_add_f32_e32 v25, v25, v25
	v_sub_f32_e32 v25, 1.0, v25
	v_mul_f32_e32 v26, 0.5, v27
	v_add_f32_e32 v25, 1.0, v25
	v_mul_f32_e32 v25, v26, v25
	v_cvt_pk_bf16_f32 v31, v24, v25
	v_mul_f32_e32 v25, 0x3d372713, v20
	v_mul_f32_e32 v25, v20, v25
	v_fma_f32 v25, v20, v25, v20
	v_mul_f32_e32 v25, 0x3f4c422a, v25
	v_add_f32_e32 v25, v25, v25
	v_mul_f32_e32 v25, 0x3fb8aa3b, v25
	v_exp_f32_e32 v26, v25
	v_or_b32_e32 v32, 0x200, v64
	v_add_u32_e32 v24, v32, v146
	v_ashrrev_i32_e32 v25, 31, v24
	v_add_f32_e32 v26, 1.0, v26
	v_lshlrev_b64 v[24:25], 10, v[24:25]
	v_lshl_add_u64 v[24:25], s[60:61], 0, v[24:25]
	v_lshl_add_u64 v[24:25], v[24:25], 0, s[18:19]
	v_lshl_add_u64 v[24:25], v[24:25], 0, v[136:137]
	global_store_dwordx4 v[24:25], v[28:31], off
	v_mul_f32_e32 v27, 0x3d372713, v21
	v_mul_f32_e32 v27, v21, v27
	v_fma_f32 v27, v21, v27, v21
	v_mul_f32_e32 v27, 0x3f4c422a, v27
	v_add_f32_e32 v27, v27, v27
	v_mul_f32_e32 v27, 0x3fb8aa3b, v27
	v_exp_f32_e32 v27, v27
	v_rcp_f32_e32 v24, v26
	s_nop 0
	v_add_f32_e32 v24, v24, v24
	v_sub_f32_e32 v24, 1.0, v24
	v_add_f32_e32 v25, 1.0, v27
	v_mul_f32_e32 v20, 0.5, v20
	v_add_f32_e32 v24, 1.0, v24
	v_mul_f32_e32 v20, v20, v24
	v_mul_f32_e32 v26, 0x3d372713, v22
	v_mul_f32_e32 v26, v22, v26
	v_fma_f32 v26, v22, v26, v22
	v_mul_f32_e32 v26, 0x3f4c422a, v26
	v_add_f32_e32 v26, v26, v26
	v_mul_f32_e32 v26, 0x3fb8aa3b, v26
	v_exp_f32_e32 v26, v26
	v_rcp_f32_e32 v24, v25
	s_nop 0
	v_add_f32_e32 v24, v24, v24
	v_sub_f32_e32 v24, 1.0, v24
	v_add_f32_e32 v25, 1.0, v26
	v_mul_f32_e32 v21, 0.5, v21
	v_add_f32_e32 v24, 1.0, v24
	v_mul_f32_e32 v21, v21, v24
	v_cvt_pk_bf16_f32 v20, v20, v21
	v_mul_f32_e32 v26, 0x3d372713, v23
	v_mul_f32_e32 v26, v23, v26
	v_fma_f32 v26, v23, v26, v23
	v_mul_f32_e32 v26, 0x3f4c422a, v26
	v_add_f32_e32 v26, v26, v26
	v_mul_f32_e32 v26, 0x3fb8aa3b, v26
	v_exp_f32_e32 v26, v26
	v_rcp_f32_e32 v21, v25
	s_nop 0
	v_add_f32_e32 v21, v21, v21
	v_sub_f32_e32 v21, 1.0, v21
	v_add_f32_e32 v24, 1.0, v26
	v_mul_f32_e32 v22, 0.5, v22
	v_add_f32_e32 v21, 1.0, v21
	v_mul_f32_e32 v21, v22, v21
	v_mul_f32_e32 v25, 0x3d372713, v16
	v_mul_f32_e32 v25, v16, v25
	v_fma_f32 v25, v16, v25, v16
	v_mul_f32_e32 v25, 0x3f4c422a, v25
	v_add_f32_e32 v25, v25, v25
	v_mul_f32_e32 v25, 0x3fb8aa3b, v25
	v_exp_f32_e32 v25, v25
	v_rcp_f32_e32 v22, v24
	s_nop 0
	v_add_f32_e32 v22, v22, v22
	v_sub_f32_e32 v22, 1.0, v22
	v_add_f32_e32 v24, 1.0, v25
	v_mul_f32_e32 v23, 0.5, v23
	v_add_f32_e32 v22, 1.0, v22
	v_mul_f32_e32 v22, v23, v22
	v_cvt_pk_bf16_f32 v21, v21, v22
	v_mul_f32_e32 v25, 0x3d372713, v17
	v_mul_f32_e32 v25, v17, v25
	v_fma_f32 v25, v17, v25, v17
	v_mul_f32_e32 v25, 0x3f4c422a, v25
	v_add_f32_e32 v25, v25, v25
	v_mul_f32_e32 v25, 0x3fb8aa3b, v25
	v_exp_f32_e32 v25, v25
	v_rcp_f32_e32 v22, v24
	s_nop 0
	v_add_f32_e32 v22, v22, v22
	v_sub_f32_e32 v22, 1.0, v22
	v_add_f32_e32 v23, 1.0, v25
	v_mul_f32_e32 v16, 0.5, v16
	v_add_f32_e32 v22, 1.0, v22
	v_mul_f32_e32 v16, v16, v22
	v_mul_f32_e32 v24, 0x3d372713, v18
	v_mul_f32_e32 v24, v18, v24
	v_fma_f32 v24, v18, v24, v18
	v_mul_f32_e32 v24, 0x3f4c422a, v24
	v_add_f32_e32 v24, v24, v24
	v_mul_f32_e32 v24, 0x3fb8aa3b, v24
	v_exp_f32_e32 v24, v24
	v_rcp_f32_e32 v22, v23
	s_nop 0
	v_add_f32_e32 v22, v22, v22
	v_sub_f32_e32 v22, 1.0, v22
	v_add_f32_e32 v23, 1.0, v24
	v_mul_f32_e32 v17, 0.5, v17
	v_add_f32_e32 v22, 1.0, v22
	v_mul_f32_e32 v17, v17, v22
	v_cvt_pk_bf16_f32 v22, v16, v17
	v_mul_f32_e32 v24, 0x3d372713, v19
	v_mul_f32_e32 v24, v19, v24
	v_fma_f32 v24, v19, v24, v19
	v_mul_f32_e32 v24, 0x3f4c422a, v24
	v_add_f32_e32 v24, v24, v24
	v_mul_f32_e32 v24, 0x3fb8aa3b, v24
	v_exp_f32_e32 v24, v24
	v_rcp_f32_e32 v16, v23
	s_nop 0
	v_add_f32_e32 v16, v16, v16
	v_sub_f32_e32 v16, 1.0, v16
	v_add_f32_e32 v17, 1.0, v24
	v_mul_f32_e32 v18, 0.5, v18
	v_add_f32_e32 v16, 1.0, v16
	v_mul_f32_e32 v16, v18, v16
	v_rcp_f32_e32 v17, v17
	s_nop 0
	v_add_f32_e32 v17, v17, v17
	v_sub_f32_e32 v17, 1.0, v17
	v_mul_f32_e32 v18, 0.5, v19
	v_add_f32_e32 v17, 1.0, v17
	v_mul_f32_e32 v17, v18, v17
	v_mul_f32_e32 v18, 0x3d372713, v12
	v_mul_f32_e32 v18, v12, v18
	v_fma_f32 v18, v12, v18, v12
	v_mul_f32_e32 v18, 0x3f4c422a, v18
	v_add_f32_e32 v18, v18, v18
	v_mul_f32_e32 v18, 0x3fb8aa3b, v18
	v_exp_f32_e32 v18, v18
	v_cvt_pk_bf16_f32 v23, v16, v17
	v_add_u32_e32 v16, v32, v147
	v_ashrrev_i32_e32 v17, 31, v16
	v_add_f32_e32 v18, 1.0, v18
	v_lshlrev_b64 v[16:17], 10, v[16:17]
	v_lshl_add_u64 v[16:17], s[60:61], 0, v[16:17]
	v_lshl_add_u64 v[16:17], v[16:17], 0, s[18:19]
	v_lshl_add_u64 v[16:17], v[16:17], 0, v[136:137]
	global_store_dwordx4 v[16:17], v[20:23], off
	v_mul_f32_e32 v19, 0x3d372713, v13
	v_mul_f32_e32 v19, v13, v19
	v_fma_f32 v19, v13, v19, v13
	v_mul_f32_e32 v19, 0x3f4c422a, v19
	v_add_f32_e32 v19, v19, v19
	v_mul_f32_e32 v19, 0x3fb8aa3b, v19
	v_exp_f32_e32 v19, v19
	v_rcp_f32_e32 v17, v18
	s_nop 0
	v_add_f32_e32 v17, v17, v17
	v_sub_f32_e32 v17, 1.0, v17
	v_add_f32_e32 v18, 1.0, v19
	v_mul_f32_e32 v12, 0.5, v12
	v_add_f32_e32 v17, 1.0, v17
	v_mul_f32_e32 v12, v12, v17
	v_mul_f32_e32 v19, 0x3d372713, v14
	v_mul_f32_e32 v19, v14, v19
	v_fma_f32 v19, v14, v19, v14
	v_mul_f32_e32 v19, 0x3f4c422a, v19
	v_add_f32_e32 v19, v19, v19
	v_mul_f32_e32 v19, 0x3fb8aa3b, v19
	v_exp_f32_e32 v19, v19
	v_rcp_f32_e32 v17, v18
	s_nop 0
	v_add_f32_e32 v17, v17, v17
	v_sub_f32_e32 v17, 1.0, v17
	v_add_f32_e32 v18, 1.0, v19
	v_mul_f32_e32 v13, 0.5, v13
	v_add_f32_e32 v17, 1.0, v17
	v_mul_f32_e32 v13, v13, v17
	v_cvt_pk_bf16_f32 v12, v12, v13
	v_mul_f32_e32 v19, 0x3d372713, v15
	v_mul_f32_e32 v19, v15, v19
	v_fma_f32 v19, v15, v19, v15
	v_mul_f32_e32 v19, 0x3f4c422a, v19
	v_add_f32_e32 v19, v19, v19
	v_mul_f32_e32 v19, 0x3fb8aa3b, v19
	v_exp_f32_e32 v19, v19
	v_rcp_f32_e32 v13, v18
	s_nop 0
	v_add_f32_e32 v13, v13, v13
	v_sub_f32_e32 v13, 1.0, v13
	v_add_f32_e32 v17, 1.0, v19
	v_mul_f32_e32 v14, 0.5, v14
	v_add_f32_e32 v13, 1.0, v13
	v_mul_f32_e32 v13, v14, v13
	v_mul_f32_e32 v18, 0x3d372713, v8
	v_mul_f32_e32 v18, v8, v18
	v_fma_f32 v18, v8, v18, v8
	v_mul_f32_e32 v18, 0x3f4c422a, v18
	v_add_f32_e32 v18, v18, v18
	v_mul_f32_e32 v18, 0x3fb8aa3b, v18
	v_exp_f32_e32 v18, v18
	v_rcp_f32_e32 v14, v17
	s_nop 0
	v_add_f32_e32 v14, v14, v14
	v_sub_f32_e32 v14, 1.0, v14
	v_add_f32_e32 v17, 1.0, v18
	v_mul_f32_e32 v15, 0.5, v15
	v_add_f32_e32 v14, 1.0, v14
	v_mul_f32_e32 v14, v15, v14
	v_cvt_pk_bf16_f32 v13, v13, v14
	v_mul_f32_e32 v18, 0x3d372713, v9
	v_mul_f32_e32 v18, v9, v18
	v_fma_f32 v18, v9, v18, v9
	v_mul_f32_e32 v18, 0x3f4c422a, v18
	v_add_f32_e32 v18, v18, v18
	v_mul_f32_e32 v18, 0x3fb8aa3b, v18
	v_exp_f32_e32 v18, v18
	v_rcp_f32_e32 v14, v17
	s_nop 0
	v_add_f32_e32 v14, v14, v14
	v_sub_f32_e32 v14, 1.0, v14
	v_add_f32_e32 v15, 1.0, v18
	v_mul_f32_e32 v8, 0.5, v8
	v_add_f32_e32 v14, 1.0, v14
	v_mul_f32_e32 v8, v8, v14
	v_mul_f32_e32 v17, 0x3d372713, v10
	v_mul_f32_e32 v17, v10, v17
	v_fma_f32 v17, v10, v17, v10
	v_mul_f32_e32 v17, 0x3f4c422a, v17
	v_add_f32_e32 v17, v17, v17
	v_mul_f32_e32 v17, 0x3fb8aa3b, v17
	v_exp_f32_e32 v17, v17
	v_rcp_f32_e32 v14, v15
	s_nop 0
	v_add_f32_e32 v14, v14, v14
	v_sub_f32_e32 v14, 1.0, v14
	v_add_f32_e32 v15, 1.0, v17
	v_mul_f32_e32 v9, 0.5, v9
	v_add_f32_e32 v14, 1.0, v14
	v_mul_f32_e32 v9, v9, v14
	v_cvt_pk_bf16_f32 v14, v8, v9
	v_mul_f32_e32 v17, 0x3d372713, v11
	v_mul_f32_e32 v17, v11, v17
	v_fma_f32 v17, v11, v17, v11
	v_mul_f32_e32 v17, 0x3f4c422a, v17
	v_add_f32_e32 v17, v17, v17
	v_mul_f32_e32 v17, 0x3fb8aa3b, v17
	v_exp_f32_e32 v17, v17
	v_rcp_f32_e32 v8, v15
	s_nop 0
	v_add_f32_e32 v8, v8, v8
	v_sub_f32_e32 v8, 1.0, v8
	v_add_f32_e32 v9, 1.0, v17
	v_mul_f32_e32 v10, 0.5, v10
	v_add_f32_e32 v8, 1.0, v8
	v_mul_f32_e32 v8, v10, v8
	v_rcp_f32_e32 v9, v9
	s_nop 0
	v_add_f32_e32 v9, v9, v9
	v_sub_f32_e32 v9, 1.0, v9
	v_mul_f32_e32 v10, 0.5, v11
	v_add_f32_e32 v9, 1.0, v9
	v_mul_f32_e32 v9, v10, v9
	v_cvt_pk_bf16_f32 v15, v8, v9
	v_mul_f32_e32 v9, 0x3d372713, v4
	v_mul_f32_e32 v9, v4, v9
	v_fma_f32 v9, v4, v9, v4
	v_mul_f32_e32 v9, 0x3f4c422a, v9
	v_add_f32_e32 v9, v9, v9
	v_mul_f32_e32 v9, 0x3fb8aa3b, v9
	v_exp_f32_e32 v10, v9
	v_or_b32_e32 v16, 0x300, v64
	v_add_u32_e32 v8, v16, v146
	v_ashrrev_i32_e32 v9, 31, v8
	v_add_f32_e32 v10, 1.0, v10
	v_lshlrev_b64 v[8:9], 10, v[8:9]
	v_lshl_add_u64 v[8:9], s[60:61], 0, v[8:9]
	v_lshl_add_u64 v[8:9], v[8:9], 0, s[18:19]
	v_lshl_add_u64 v[8:9], v[8:9], 0, v[136:137]
	global_store_dwordx4 v[8:9], v[12:15], off
	v_mul_f32_e32 v11, 0x3d372713, v5
	v_mul_f32_e32 v11, v5, v11
	v_fma_f32 v11, v5, v11, v5
	v_mul_f32_e32 v11, 0x3f4c422a, v11
	v_add_f32_e32 v11, v11, v11
	v_mul_f32_e32 v11, 0x3fb8aa3b, v11
	v_exp_f32_e32 v11, v11
	v_rcp_f32_e32 v8, v10
	s_nop 0
	v_add_f32_e32 v8, v8, v8
	v_sub_f32_e32 v8, 1.0, v8
	v_add_f32_e32 v9, 1.0, v11
	v_mul_f32_e32 v4, 0.5, v4
	v_add_f32_e32 v8, 1.0, v8
	v_mul_f32_e32 v4, v4, v8
	v_mul_f32_e32 v10, 0x3d372713, v6
	v_mul_f32_e32 v10, v6, v10
	v_fma_f32 v10, v6, v10, v6
	v_mul_f32_e32 v10, 0x3f4c422a, v10
	v_add_f32_e32 v10, v10, v10
	v_mul_f32_e32 v10, 0x3fb8aa3b, v10
	v_exp_f32_e32 v10, v10
	v_rcp_f32_e32 v8, v9
	s_nop 0
	v_add_f32_e32 v8, v8, v8
	v_sub_f32_e32 v8, 1.0, v8
	v_add_f32_e32 v9, 1.0, v10
	v_mul_f32_e32 v5, 0.5, v5
	v_add_f32_e32 v8, 1.0, v8
	v_mul_f32_e32 v5, v5, v8
	v_cvt_pk_bf16_f32 v4, v4, v5
	v_mul_f32_e32 v10, 0x3d372713, v7
	v_mul_f32_e32 v10, v7, v10
	v_fma_f32 v10, v7, v10, v7
	v_mul_f32_e32 v10, 0x3f4c422a, v10
	v_add_f32_e32 v10, v10, v10
	v_mul_f32_e32 v10, 0x3fb8aa3b, v10
	v_exp_f32_e32 v10, v10
	v_rcp_f32_e32 v5, v9
	s_nop 0
	v_add_f32_e32 v5, v5, v5
	v_sub_f32_e32 v5, 1.0, v5
	v_add_f32_e32 v8, 1.0, v10
	v_mul_f32_e32 v6, 0.5, v6
	v_add_f32_e32 v5, 1.0, v5
	v_mul_f32_e32 v5, v6, v5
	v_mul_f32_e32 v9, 0x3d372713, v0
	v_mul_f32_e32 v9, v0, v9
	v_fma_f32 v9, v0, v9, v0
	v_mul_f32_e32 v9, 0x3f4c422a, v9
	v_add_f32_e32 v9, v9, v9
	v_mul_f32_e32 v9, 0x3fb8aa3b, v9
	v_exp_f32_e32 v9, v9
	v_rcp_f32_e32 v6, v8
	s_nop 0
	v_add_f32_e32 v6, v6, v6
	v_sub_f32_e32 v6, 1.0, v6
	v_add_f32_e32 v8, 1.0, v9
	v_mul_f32_e32 v7, 0.5, v7
	v_add_f32_e32 v6, 1.0, v6
	v_mul_f32_e32 v6, v7, v6
	v_cvt_pk_bf16_f32 v5, v5, v6
	v_mul_f32_e32 v9, 0x3d372713, v1
	v_mul_f32_e32 v9, v1, v9
	v_fma_f32 v9, v1, v9, v1
	v_mul_f32_e32 v9, 0x3f4c422a, v9
	v_add_f32_e32 v9, v9, v9
	v_mul_f32_e32 v9, 0x3fb8aa3b, v9
	v_exp_f32_e32 v9, v9
	v_rcp_f32_e32 v6, v8
	s_nop 0
	v_add_f32_e32 v6, v6, v6
	v_sub_f32_e32 v6, 1.0, v6
	v_add_f32_e32 v7, 1.0, v9
	v_mul_f32_e32 v0, 0.5, v0
	v_add_f32_e32 v6, 1.0, v6
	v_mul_f32_e32 v0, v0, v6
	v_mul_f32_e32 v8, 0x3d372713, v2
	v_mul_f32_e32 v8, v2, v8
	v_fma_f32 v8, v2, v8, v2
	v_mul_f32_e32 v8, 0x3f4c422a, v8
	v_add_f32_e32 v8, v8, v8
	v_mul_f32_e32 v8, 0x3fb8aa3b, v8
	v_exp_f32_e32 v8, v8
	v_rcp_f32_e32 v6, v7
	s_nop 0
	v_add_f32_e32 v6, v6, v6
	v_sub_f32_e32 v6, 1.0, v6
	v_add_f32_e32 v7, 1.0, v8
	v_mul_f32_e32 v1, 0.5, v1
	v_add_f32_e32 v6, 1.0, v6
	v_mul_f32_e32 v1, v1, v6
	v_cvt_pk_bf16_f32 v6, v0, v1
	v_mul_f32_e32 v8, 0x3d372713, v3
	v_mul_f32_e32 v8, v3, v8
	v_fma_f32 v8, v3, v8, v3
	v_mul_f32_e32 v8, 0x3f4c422a, v8
	v_add_f32_e32 v8, v8, v8
	v_mul_f32_e32 v8, 0x3fb8aa3b, v8
	v_exp_f32_e32 v8, v8
	v_rcp_f32_e32 v0, v7
	s_nop 0
	v_add_f32_e32 v0, v0, v0
	v_sub_f32_e32 v0, 1.0, v0
	v_add_f32_e32 v1, 1.0, v8
	v_mul_f32_e32 v2, 0.5, v2
	v_add_f32_e32 v0, 1.0, v0
	v_mul_f32_e32 v0, v2, v0
	v_rcp_f32_e32 v1, v1
	s_nop 0
	v_add_f32_e32 v1, v1, v1
	v_sub_f32_e32 v1, 1.0, v1
	v_mul_f32_e32 v2, 0.5, v3
	v_add_f32_e32 v1, 1.0, v1
	v_mul_f32_e32 v1, v2, v1
	v_cvt_pk_bf16_f32 v7, v0, v1
	v_add_u32_e32 v0, v16, v147
	v_ashrrev_i32_e32 v1, 31, v0
	v_lshlrev_b64 v[0:1], 10, v[0:1]
	v_lshl_add_u64 v[0:1], s[60:61], 0, v[0:1]
	v_lshl_add_u64 v[0:1], v[0:1], 0, s[18:19]
	v_lshl_add_u64 v[0:1], v[0:1], 0, v[136:137]
	s_andn2_b64 vcc, exec, s[6:7]
	s_mov_b64 s[6:7], -1
	global_store_dwordx4 v[0:1], v[4:7], off
	s_cbranch_vccnz .LBB0_915
	s_and_b64 vcc, exec, s[4:5]
	s_cbranch_vccnz .LBB0_914
	s_barrier
	s_branch .LBB0_914

.LBB0_1431:
	v_lshl_add_u32 v146, s1, 8, v154
	v_ashrrev_i32_e32 v147, 31, v146
	v_lshl_add_u64 v[144:145], v[146:147], 2, s[12:13]
	flat_load_dwordx4 v[158:161], v[144:145]
	flat_load_dwordx4 v[162:165], v[144:145] offset:16
	v_lshl_add_u32 v148, s0, 8, v152
	v_ashrrev_i32_e32 v149, 31, v148
	v_lshlrev_b64 v[150:151], 10, v[148:149]
	v_lshlrev_b64 v[146:147], 1, v[146:147]
	v_lshl_add_u64 v[150:151], s[60:61], 0, v[150:151]
	v_lshl_add_u64 v[150:151], v[150:151], 0, v[146:147]
	global_load_dwordx4 v[166:169], v[150:151], off
	s_waitcnt vmcnt(0) lgkmcnt(0)
	v_add_f32_e32 v124, v124, v158
	v_add_f32_e32 v120, v120, v162
	v_mul_f32_e32 v124, 0xbfb8aa3b, v124
	v_add_f32_e32 v125, v125, v159
	v_add_f32_e32 v126, v126, v160
	v_mul_f32_e32 v120, 0xbfb8aa3b, v120
	v_exp_f32_e32 v124, v124
	v_add_f32_e32 v121, v121, v163
	v_mul_f32_e32 v125, 0xbfb8aa3b, v125
	v_mul_f32_e32 v126, 0xbfb8aa3b, v126
	v_exp_f32_e32 v120, v120
	v_mul_f32_e32 v121, 0xbfb8aa3b, v121
	v_exp_f32_e32 v125, v125
	v_exp_f32_e32 v126, v126
	v_exp_f32_e32 v121, v121
	v_add_f32_e32 v124, 1.0, v124
	v_lshlrev_b32_e32 v158, 16, v166
	v_and_b32_e32 v159, 0xffff0000, v166
	v_lshlrev_b32_e32 v160, 16, v167
	v_and_b32_e32 v162, 0xffff0000, v167
	v_lshlrev_b32_e32 v163, 16, v168
	v_and_b32_e32 v166, 0xffff0000, v168
	v_lshlrev_b32_e32 v167, 16, v169
	v_and_b32_e32 v168, 0xffff0000, v169
	v_add_f32_e32 v120, 1.0, v120
	v_add_f32_e32 v125, 1.0, v125
	v_add_f32_e32 v126, 1.0, v126
	v_add_f32_e32 v121, 1.0, v121
	v_add_f32_e32 v122, v122, v164
	v_mul_f32_e32 v122, 0xbfb8aa3b, v122
	v_exp_f32_e32 v122, v122
	v_rcp_f32_e32 v124, v124
	s_nop 0
	v_mul_f32_e32 v124, v124, v158
	v_rcp_f32_e32 v120, v120
	s_nop 0
	v_mul_f32_e32 v163, v120, v163
	v_rcp_f32_e32 v120, v125
	v_rcp_f32_e32 v121, v121
	v_add_f32_e32 v122, 1.0, v122
	v_mul_f32_e32 v120, v120, v159
	v_mul_f32_e32 v125, v121, v166
	v_add_f32_e32 v127, v127, v161
	v_mul_f32_e32 v127, 0xbfb8aa3b, v127
	v_rcp_f32_e32 v121, v126
	v_exp_f32_e32 v127, v127
	v_mul_f32_e32 v121, v121, v160
	v_add_f32_e32 v127, 1.0, v127
	v_add_f32_e32 v123, v123, v165
	v_rcp_f32_e32 v122, v122
	v_mul_f32_e32 v123, 0xbfb8aa3b, v123
	v_mul_f32_e32 v126, v122, v167
	v_exp_f32_e32 v123, v123
	s_nop 0
	v_add_f32_e32 v123, 1.0, v123
	v_rcp_f32_e32 v122, v127
	s_nop 0
	v_mul_f32_e32 v122, v122, v162
	v_rcp_f32_e32 v123, v123
	s_nop 0
	v_mul_f32_e32 v123, v123, v168
	v_cvt_pk_bf16_f32 v120, v124, v120
	v_cvt_pk_bf16_f32 v121, v121, v122
	v_cvt_pk_bf16_f32 v122, v163, v125
	v_cvt_pk_bf16_f32 v123, v126, v123
	global_load_dwordx4 v[124:127], v[150:151], off offset:256
	v_lshlrev_b64 v[150:151], 11, v[148:149]
	v_lshl_add_u64 v[150:151], s[48:49], 0, v[150:151]
	v_lshl_add_u64 v[150:151], v[150:151], 0, v[146:147]
	global_store_dwordx4 v[150:151], v[120:123], off offset:1024
	flat_load_dwordx4 v[120:123], v[144:145] offset:512
	s_nop 0
	flat_load_dwordx4 v[158:161], v[144:145] offset:528
	s_waitcnt vmcnt(0)
	v_lshlrev_b32_e32 v149, 16, v124
	v_lshlrev_b32_e32 v163, 16, v126
	v_and_b32_e32 v124, 0xffff0000, v124
	v_and_b32_e32 v126, 0xffff0000, v126
	s_waitcnt lgkmcnt(0)
	v_add_f32_e32 v116, v116, v120
	v_mul_f32_e32 v116, 0xbfb8aa3b, v116
	v_exp_f32_e32 v116, v116
	v_add_f32_e32 v112, v112, v158
	v_mul_f32_e32 v112, 0xbfb8aa3b, v112
	v_exp_f32_e32 v112, v112
	v_add_f32_e32 v116, 1.0, v116
	v_add_f32_e32 v112, 1.0, v112
	v_add_f32_e32 v117, v117, v121
	v_mul_f32_e32 v117, 0xbfb8aa3b, v117
	v_exp_f32_e32 v117, v117
	v_rcp_f32_e32 v116, v116
	s_nop 0
	v_mul_f32_e32 v116, v116, v149
	v_add_f32_e32 v117, 1.0, v117
	v_add_f32_e32 v113, v113, v159
	v_rcp_f32_e32 v112, v112
	v_mul_f32_e32 v113, 0xbfb8aa3b, v113
	v_mul_f32_e32 v120, v112, v163
	v_exp_f32_e32 v113, v113
	s_nop 0
	v_add_f32_e32 v113, 1.0, v113
	v_add_f32_e32 v118, v118, v122
	v_mul_f32_e32 v118, 0xbfb8aa3b, v118
	v_rcp_f32_e32 v112, v117
	v_exp_f32_e32 v118, v118
	v_mul_f32_e32 v112, v112, v124
	v_add_f32_e32 v118, 1.0, v118
	v_add_f32_e32 v114, v114, v160
	v_rcp_f32_e32 v113, v113
	v_mul_f32_e32 v114, 0xbfb8aa3b, v114
	v_mul_f32_e32 v117, v113, v126
	v_exp_f32_e32 v114, v114
	s_nop 0
	v_add_f32_e32 v114, 1.0, v114
	v_add_f32_e32 v119, v119, v123
	v_mul_f32_e32 v119, 0xbfb8aa3b, v119
	v_rcp_f32_e32 v113, v118
	v_exp_f32_e32 v119, v119
	s_nop 0
	v_add_f32_e32 v119, 1.0, v119
	v_add_f32_e32 v115, v115, v161
	v_lshlrev_b32_e32 v164, 16, v127
	v_rcp_f32_e32 v114, v114
	v_mul_f32_e32 v115, 0xbfb8aa3b, v115
	v_mul_f32_e32 v118, v114, v164
	v_exp_f32_e32 v115, v115
	s_nop 0
	v_add_f32_e32 v115, 1.0, v115
	v_rcp_f32_e32 v114, v119
	v_lshlrev_b32_e32 v162, 16, v125
	v_and_b32_e32 v125, 0xffff0000, v125
	v_or_b32_e32 v124, 16, v148
	v_mul_f32_e32 v113, v113, v162
	v_mul_f32_e32 v114, v114, v125
	v_ashrrev_i32_e32 v125, 31, v124
	v_and_b32_e32 v127, 0xffff0000, v127
	v_rcp_f32_e32 v115, v115
	v_cvt_pk_bf16_f32 v112, v116, v112
	v_cvt_pk_bf16_f32 v113, v113, v114
	v_cvt_pk_bf16_f32 v114, v120, v117
	v_lshlrev_b64 v[116:117], 10, v[124:125]
	v_mul_f32_e32 v115, v115, v127
	v_lshl_add_u64 v[116:117], s[60:61], 0, v[116:117]
	v_cvt_pk_bf16_f32 v115, v118, v115
	v_lshl_add_u64 v[126:127], v[116:117], 0, v[146:147]
	global_store_dwordx4 v[150:151], v[112:115], off offset:1280
	global_load_dwordx4 v[116:119], v[126:127], off
	s_nop 0
	flat_load_dwordx4 v[112:115], v[144:145]
	flat_load_dwordx4 v[120:123], v[144:145] offset:16
	v_lshlrev_b64 v[124:125], 11, v[124:125]
	s_waitcnt vmcnt(0) lgkmcnt(0)
	v_add_f32_e32 v108, v108, v112
	v_mul_f32_e32 v108, 0xbfb8aa3b, v108
	v_exp_f32_e32 v108, v108
	v_add_f32_e32 v104, v104, v120
	v_mul_f32_e32 v104, 0xbfb8aa3b, v104
	v_exp_f32_e32 v104, v104
	v_add_f32_e32 v108, 1.0, v108
	v_add_f32_e32 v104, 1.0, v104
	v_add_f32_e32 v109, v109, v113
	v_mul_f32_e32 v109, 0xbfb8aa3b, v109
	v_rcp_f32_e32 v108, v108
	v_exp_f32_e32 v109, v109
	v_lshlrev_b32_e32 v149, 16, v116
	v_mul_f32_e32 v108, v108, v149
	v_add_f32_e32 v109, 1.0, v109
	v_add_f32_e32 v105, v105, v121
	v_lshlrev_b32_e32 v150, 16, v118
	v_rcp_f32_e32 v104, v104
	v_mul_f32_e32 v105, 0xbfb8aa3b, v105
	v_mul_f32_e32 v113, v104, v150
	v_exp_f32_e32 v105, v105
	s_nop 0
	v_add_f32_e32 v105, 1.0, v105
	v_add_f32_e32 v110, v110, v114
	v_mul_f32_e32 v110, 0xbfb8aa3b, v110
	v_exp_f32_e32 v110, v110
	v_rcp_f32_e32 v104, v109
	v_and_b32_e32 v116, 0xffff0000, v116
	v_mul_f32_e32 v104, v104, v116
	v_add_f32_e32 v110, 1.0, v110
	v_add_f32_e32 v106, v106, v122
	v_and_b32_e32 v118, 0xffff0000, v118
	v_rcp_f32_e32 v105, v105
	v_mul_f32_e32 v106, 0xbfb8aa3b, v106
	v_mul_f32_e32 v109, v105, v118
	v_exp_f32_e32 v106, v106
	s_nop 0
	v_add_f32_e32 v106, 1.0, v106
	v_add_f32_e32 v111, v111, v115
	v_mul_f32_e32 v111, 0xbfb8aa3b, v111
	v_rcp_f32_e32 v105, v110
	v_exp_f32_e32 v111, v111
	v_lshlrev_b32_e32 v112, 16, v117
	v_mul_f32_e32 v105, v105, v112
	v_add_f32_e32 v111, 1.0, v111
	v_add_f32_e32 v107, v107, v123
	v_lshlrev_b32_e32 v159, 16, v119
	v_rcp_f32_e32 v106, v106
	v_mul_f32_e32 v107, 0xbfb8aa3b, v107
	v_mul_f32_e32 v110, v106, v159
	v_exp_f32_e32 v107, v107
	s_nop 0
	v_add_f32_e32 v107, 1.0, v107
	v_rcp_f32_e32 v106, v111
	v_and_b32_e32 v117, 0xffff0000, v117
	v_mul_f32_e32 v106, v106, v117
	v_and_b32_e32 v119, 0xffff0000, v119
	v_rcp_f32_e32 v107, v107
	v_cvt_pk_bf16_f32 v104, v108, v104
	v_cvt_pk_bf16_f32 v105, v105, v106
	v_cvt_pk_bf16_f32 v106, v113, v109
	v_lshl_add_u64 v[108:109], s[48:49], 0, v[124:125]
	v_mul_f32_e32 v107, v107, v119
	v_lshl_add_u64 v[116:117], v[108:109], 0, v[146:147]
	v_cvt_pk_bf16_f32 v107, v110, v107
	global_store_dwordx4 v[116:117], v[104:107], off offset:1024
	global_load_dwordx4 v[108:111], v[126:127], off offset:256
	s_nop 0
	flat_load_dwordx4 v[104:107], v[144:145] offset:512
	flat_load_dwordx4 v[112:115], v[144:145] offset:528
	s_waitcnt vmcnt(0) lgkmcnt(0)
	v_add_f32_e32 v100, v100, v104
	v_mul_f32_e32 v100, 0xbfb8aa3b, v100
	v_exp_f32_e32 v100, v100
	v_add_f32_e32 v96, v96, v112
	v_mul_f32_e32 v96, 0xbfb8aa3b, v96
	v_exp_f32_e32 v96, v96
	v_add_f32_e32 v100, 1.0, v100
	v_add_f32_e32 v96, 1.0, v96
	v_add_f32_e32 v101, v101, v105
	v_mul_f32_e32 v101, 0xbfb8aa3b, v101
	v_rcp_f32_e32 v100, v100
	v_exp_f32_e32 v101, v101
	v_lshlrev_b32_e32 v118, 16, v108
	v_mul_f32_e32 v100, v100, v118
	v_add_f32_e32 v101, 1.0, v101
	v_add_f32_e32 v97, v97, v113
	v_lshlrev_b32_e32 v119, 16, v110
	v_rcp_f32_e32 v96, v96
	v_mul_f32_e32 v97, 0xbfb8aa3b, v97
	v_mul_f32_e32 v105, v96, v119
	v_exp_f32_e32 v97, v97
	s_nop 0
	v_add_f32_e32 v97, 1.0, v97
	v_add_f32_e32 v102, v102, v106
	v_mul_f32_e32 v102, 0xbfb8aa3b, v102
	v_exp_f32_e32 v102, v102
	v_rcp_f32_e32 v96, v101
	v_and_b32_e32 v108, 0xffff0000, v108
	v_mul_f32_e32 v96, v96, v108
	v_add_f32_e32 v102, 1.0, v102
	v_add_f32_e32 v98, v98, v114
	v_and_b32_e32 v110, 0xffff0000, v110
	v_rcp_f32_e32 v97, v97
	v_mul_f32_e32 v98, 0xbfb8aa3b, v98
	v_mul_f32_e32 v101, v97, v110
	v_exp_f32_e32 v98, v98
	s_nop 0
	v_add_f32_e32 v98, 1.0, v98
	v_add_f32_e32 v103, v103, v107
	v_mul_f32_e32 v103, 0xbfb8aa3b, v103
	v_rcp_f32_e32 v97, v102
	v_exp_f32_e32 v103, v103
	v_lshlrev_b32_e32 v104, 16, v109
	v_mul_f32_e32 v97, v97, v104
	v_add_f32_e32 v103, 1.0, v103
	v_add_f32_e32 v99, v99, v115
	v_lshlrev_b32_e32 v122, 16, v111
	v_rcp_f32_e32 v98, v98
	v_mul_f32_e32 v99, 0xbfb8aa3b, v99
	v_mul_f32_e32 v102, v98, v122
	v_exp_f32_e32 v99, v99
	s_nop 0
	v_add_f32_e32 v99, 1.0, v99
	v_rcp_f32_e32 v98, v103
	v_and_b32_e32 v109, 0xffff0000, v109
	v_or_b32_e32 v108, 32, v148
	v_mul_f32_e32 v98, v98, v109
	v_ashrrev_i32_e32 v109, 31, v108
	v_and_b32_e32 v111, 0xffff0000, v111
	v_rcp_f32_e32 v99, v99
	v_cvt_pk_bf16_f32 v96, v100, v96
	v_cvt_pk_bf16_f32 v97, v97, v98
	v_cvt_pk_bf16_f32 v98, v105, v101
	v_lshlrev_b64 v[100:101], 10, v[108:109]
	v_mul_f32_e32 v99, v99, v111
	v_lshl_add_u64 v[100:101], s[60:61], 0, v[100:101]
	v_cvt_pk_bf16_f32 v99, v102, v99
	v_lshl_add_u64 v[110:111], v[100:101], 0, v[146:147]
	global_store_dwordx4 v[116:117], v[96:99], off offset:1280
	global_load_dwordx4 v[100:103], v[110:111], off
	s_nop 0
	flat_load_dwordx4 v[96:99], v[144:145]
	flat_load_dwordx4 v[104:107], v[144:145] offset:16
	v_lshlrev_b64 v[108:109], 11, v[108:109]
	s_waitcnt vmcnt(0) lgkmcnt(0)
	v_add_f32_e32 v92, v92, v96
	v_mul_f32_e32 v92, 0xbfb8aa3b, v92
	v_exp_f32_e32 v92, v92
	v_add_f32_e32 v88, v88, v104
	v_mul_f32_e32 v88, 0xbfb8aa3b, v88
	v_exp_f32_e32 v88, v88
	v_add_f32_e32 v92, 1.0, v92
	v_add_f32_e32 v88, 1.0, v88
	v_add_f32_e32 v93, v93, v97
	v_mul_f32_e32 v93, 0xbfb8aa3b, v93
	v_rcp_f32_e32 v92, v92
	v_exp_f32_e32 v93, v93
	v_lshlrev_b32_e32 v112, 16, v100
	v_mul_f32_e32 v92, v92, v112
	v_add_f32_e32 v93, 1.0, v93
	v_add_f32_e32 v89, v89, v105
	v_lshlrev_b32_e32 v113, 16, v102
	v_rcp_f32_e32 v88, v88
	v_mul_f32_e32 v89, 0xbfb8aa3b, v89
	v_mul_f32_e32 v97, v88, v113
	v_exp_f32_e32 v89, v89
	s_nop 0
	v_add_f32_e32 v89, 1.0, v89
	v_add_f32_e32 v94, v94, v98
	v_mul_f32_e32 v94, 0xbfb8aa3b, v94
	v_exp_f32_e32 v94, v94
	v_rcp_f32_e32 v88, v93
	v_and_b32_e32 v100, 0xffff0000, v100
	v_mul_f32_e32 v88, v88, v100
	v_add_f32_e32 v94, 1.0, v94
	v_add_f32_e32 v90, v90, v106
	v_and_b32_e32 v102, 0xffff0000, v102
	v_rcp_f32_e32 v89, v89
	v_mul_f32_e32 v90, 0xbfb8aa3b, v90
	v_mul_f32_e32 v93, v89, v102
	v_exp_f32_e32 v90, v90
	s_nop 0
	v_add_f32_e32 v90, 1.0, v90
	v_add_f32_e32 v95, v95, v99
	v_mul_f32_e32 v95, 0xbfb8aa3b, v95
	v_rcp_f32_e32 v89, v94
	v_exp_f32_e32 v95, v95
	v_lshlrev_b32_e32 v96, 16, v101
	v_mul_f32_e32 v89, v89, v96
	v_add_f32_e32 v95, 1.0, v95
	v_add_f32_e32 v91, v91, v107
	v_lshlrev_b32_e32 v116, 16, v103
	v_rcp_f32_e32 v90, v90
	v_mul_f32_e32 v91, 0xbfb8aa3b, v91
	v_mul_f32_e32 v94, v90, v116
	v_exp_f32_e32 v91, v91
	s_nop 0
	v_add_f32_e32 v91, 1.0, v91
	v_rcp_f32_e32 v90, v95
	v_and_b32_e32 v101, 0xffff0000, v101
	v_mul_f32_e32 v90, v90, v101
	v_and_b32_e32 v103, 0xffff0000, v103
	v_rcp_f32_e32 v91, v91
	v_cvt_pk_bf16_f32 v88, v92, v88
	v_cvt_pk_bf16_f32 v89, v89, v90
	v_cvt_pk_bf16_f32 v90, v97, v93
	v_lshl_add_u64 v[92:93], s[48:49], 0, v[108:109]
	v_mul_f32_e32 v91, v91, v103
	v_lshl_add_u64 v[100:101], v[92:93], 0, v[146:147]
	v_cvt_pk_bf16_f32 v91, v94, v91
	global_store_dwordx4 v[100:101], v[88:91], off offset:1024
	global_load_dwordx4 v[92:95], v[110:111], off offset:256
	s_nop 0
	flat_load_dwordx4 v[88:91], v[144:145] offset:512
	flat_load_dwordx4 v[96:99], v[144:145] offset:528
	s_waitcnt vmcnt(0) lgkmcnt(0)
	v_add_f32_e32 v84, v84, v88
	v_mul_f32_e32 v84, 0xbfb8aa3b, v84
	v_exp_f32_e32 v84, v84
	v_add_f32_e32 v80, v80, v96
	v_mul_f32_e32 v80, 0xbfb8aa3b, v80
	v_exp_f32_e32 v80, v80
	v_add_f32_e32 v84, 1.0, v84
	v_add_f32_e32 v80, 1.0, v80
	v_add_f32_e32 v85, v85, v89
	v_mul_f32_e32 v85, 0xbfb8aa3b, v85
	v_rcp_f32_e32 v84, v84
	v_exp_f32_e32 v85, v85
	v_lshlrev_b32_e32 v102, 16, v92
	v_mul_f32_e32 v84, v84, v102
	v_add_f32_e32 v85, 1.0, v85
	v_add_f32_e32 v81, v81, v97
	v_lshlrev_b32_e32 v103, 16, v94
	v_rcp_f32_e32 v80, v80
	v_mul_f32_e32 v81, 0xbfb8aa3b, v81
	v_mul_f32_e32 v89, v80, v103
	v_exp_f32_e32 v81, v81
	s_nop 0
	v_add_f32_e32 v81, 1.0, v81
	v_add_f32_e32 v86, v86, v90
	v_mul_f32_e32 v86, 0xbfb8aa3b, v86
	v_exp_f32_e32 v86, v86
	v_rcp_f32_e32 v80, v85
	v_and_b32_e32 v92, 0xffff0000, v92
	v_mul_f32_e32 v80, v80, v92
	v_add_f32_e32 v86, 1.0, v86
	v_add_f32_e32 v82, v82, v98
	v_and_b32_e32 v94, 0xffff0000, v94
	v_rcp_f32_e32 v81, v81
	v_mul_f32_e32 v82, 0xbfb8aa3b, v82
	v_mul_f32_e32 v85, v81, v94
	v_exp_f32_e32 v82, v82
	s_nop 0
	v_add_f32_e32 v82, 1.0, v82
	v_add_f32_e32 v87, v87, v91
	v_mul_f32_e32 v87, 0xbfb8aa3b, v87
	v_rcp_f32_e32 v81, v86
	v_exp_f32_e32 v87, v87
	v_lshlrev_b32_e32 v88, 16, v93
	v_mul_f32_e32 v81, v81, v88
	v_add_f32_e32 v87, 1.0, v87
	v_add_f32_e32 v83, v83, v99
	v_lshlrev_b32_e32 v106, 16, v95
	v_rcp_f32_e32 v82, v82
	v_mul_f32_e32 v83, 0xbfb8aa3b, v83
	v_mul_f32_e32 v86, v82, v106
	v_exp_f32_e32 v83, v83
	s_nop 0
	v_add_f32_e32 v83, 1.0, v83
	v_rcp_f32_e32 v82, v87
	v_and_b32_e32 v93, 0xffff0000, v93
	v_or_b32_e32 v92, 48, v148
	v_mul_f32_e32 v82, v82, v93
	v_ashrrev_i32_e32 v93, 31, v92
	v_and_b32_e32 v95, 0xffff0000, v95
	v_rcp_f32_e32 v83, v83
	v_cvt_pk_bf16_f32 v80, v84, v80
	v_cvt_pk_bf16_f32 v81, v81, v82
	v_cvt_pk_bf16_f32 v82, v89, v85
	v_lshlrev_b64 v[84:85], 10, v[92:93]
	v_mul_f32_e32 v83, v83, v95
	v_lshl_add_u64 v[84:85], s[60:61], 0, v[84:85]
	v_cvt_pk_bf16_f32 v83, v86, v83
	v_lshl_add_u64 v[94:95], v[84:85], 0, v[146:147]
	global_store_dwordx4 v[100:101], v[80:83], off offset:1280
	global_load_dwordx4 v[84:87], v[94:95], off
	s_nop 0
	flat_load_dwordx4 v[80:83], v[144:145]
	flat_load_dwordx4 v[88:91], v[144:145] offset:16
	v_lshlrev_b64 v[92:93], 11, v[92:93]
	s_waitcnt vmcnt(0) lgkmcnt(0)
	v_add_f32_e32 v76, v76, v80
	v_mul_f32_e32 v76, 0xbfb8aa3b, v76
	v_exp_f32_e32 v76, v76
	v_add_f32_e32 v72, v72, v88
	v_mul_f32_e32 v72, 0xbfb8aa3b, v72
	v_exp_f32_e32 v72, v72
	v_add_f32_e32 v76, 1.0, v76
	v_add_f32_e32 v72, 1.0, v72
	v_add_f32_e32 v77, v77, v81
	v_mul_f32_e32 v77, 0xbfb8aa3b, v77
	v_rcp_f32_e32 v76, v76
	v_exp_f32_e32 v77, v77
	v_lshlrev_b32_e32 v96, 16, v84
	v_mul_f32_e32 v76, v76, v96
	v_add_f32_e32 v77, 1.0, v77
	v_add_f32_e32 v73, v73, v89
	v_lshlrev_b32_e32 v97, 16, v86
	v_rcp_f32_e32 v72, v72
	v_mul_f32_e32 v73, 0xbfb8aa3b, v73
	v_mul_f32_e32 v81, v72, v97
	v_exp_f32_e32 v73, v73
	s_nop 0
	v_add_f32_e32 v73, 1.0, v73
	v_add_f32_e32 v78, v78, v82
	v_mul_f32_e32 v78, 0xbfb8aa3b, v78
	v_exp_f32_e32 v78, v78
	v_rcp_f32_e32 v72, v77
	v_and_b32_e32 v84, 0xffff0000, v84
	v_mul_f32_e32 v72, v72, v84
	v_add_f32_e32 v78, 1.0, v78
	v_add_f32_e32 v74, v74, v90
	v_and_b32_e32 v86, 0xffff0000, v86
	v_rcp_f32_e32 v73, v73
	v_mul_f32_e32 v74, 0xbfb8aa3b, v74
	v_mul_f32_e32 v77, v73, v86
	v_exp_f32_e32 v74, v74
	s_nop 0
	v_add_f32_e32 v74, 1.0, v74
	v_add_f32_e32 v79, v79, v83
	v_mul_f32_e32 v79, 0xbfb8aa3b, v79
	v_rcp_f32_e32 v73, v78
	v_exp_f32_e32 v79, v79
	v_lshlrev_b32_e32 v80, 16, v85
	v_mul_f32_e32 v73, v73, v80
	v_add_f32_e32 v79, 1.0, v79
	v_add_f32_e32 v75, v75, v91
	v_lshlrev_b32_e32 v100, 16, v87
	v_rcp_f32_e32 v74, v74
	v_mul_f32_e32 v75, 0xbfb8aa3b, v75
	v_mul_f32_e32 v78, v74, v100
	v_exp_f32_e32 v75, v75
	s_nop 0
	v_add_f32_e32 v75, 1.0, v75
	v_rcp_f32_e32 v74, v79
	v_and_b32_e32 v85, 0xffff0000, v85
	v_mul_f32_e32 v74, v74, v85
	v_and_b32_e32 v87, 0xffff0000, v87
	v_rcp_f32_e32 v75, v75
	v_cvt_pk_bf16_f32 v72, v76, v72
	v_cvt_pk_bf16_f32 v73, v73, v74
	v_cvt_pk_bf16_f32 v74, v81, v77
	v_lshl_add_u64 v[76:77], s[48:49], 0, v[92:93]
	v_mul_f32_e32 v75, v75, v87
	v_lshl_add_u64 v[84:85], v[76:77], 0, v[146:147]
	v_cvt_pk_bf16_f32 v75, v78, v75
	global_store_dwordx4 v[84:85], v[72:75], off offset:1024
	global_load_dwordx4 v[76:79], v[94:95], off offset:256
	s_nop 0
	flat_load_dwordx4 v[72:75], v[144:145] offset:512
	flat_load_dwordx4 v[80:83], v[144:145] offset:528
	s_waitcnt vmcnt(0) lgkmcnt(0)
	v_add_f32_e32 v68, v68, v72
	v_mul_f32_e32 v68, 0xbfb8aa3b, v68
	v_exp_f32_e32 v68, v68
	v_add_f32_e32 v64, v64, v80
	v_mul_f32_e32 v64, 0xbfb8aa3b, v64
	v_exp_f32_e32 v64, v64
	v_add_f32_e32 v68, 1.0, v68
	v_add_f32_e32 v64, 1.0, v64
	v_add_f32_e32 v69, v69, v73
	v_mul_f32_e32 v69, 0xbfb8aa3b, v69
	v_rcp_f32_e32 v68, v68
	v_exp_f32_e32 v69, v69
	v_lshlrev_b32_e32 v86, 16, v76
	v_mul_f32_e32 v68, v68, v86
	v_add_f32_e32 v69, 1.0, v69
	v_add_f32_e32 v65, v65, v81
	v_lshlrev_b32_e32 v87, 16, v78
	v_rcp_f32_e32 v64, v64
	v_mul_f32_e32 v65, 0xbfb8aa3b, v65
	v_mul_f32_e32 v73, v64, v87
	v_exp_f32_e32 v65, v65
	s_nop 0
	v_add_f32_e32 v65, 1.0, v65
	v_add_f32_e32 v70, v70, v74
	v_mul_f32_e32 v70, 0xbfb8aa3b, v70
	v_exp_f32_e32 v70, v70
	v_rcp_f32_e32 v64, v69
	v_and_b32_e32 v76, 0xffff0000, v76
	v_mul_f32_e32 v64, v64, v76
	v_add_f32_e32 v70, 1.0, v70
	v_add_f32_e32 v66, v66, v82
	v_and_b32_e32 v78, 0xffff0000, v78
	v_rcp_f32_e32 v65, v65
	v_mul_f32_e32 v66, 0xbfb8aa3b, v66
	v_mul_f32_e32 v69, v65, v78
	v_exp_f32_e32 v66, v66
	s_nop 0
	v_add_f32_e32 v66, 1.0, v66
	v_add_f32_e32 v71, v71, v75
	v_mul_f32_e32 v71, 0xbfb8aa3b, v71
	v_rcp_f32_e32 v65, v70
	v_exp_f32_e32 v71, v71
	v_lshlrev_b32_e32 v72, 16, v77
	v_mul_f32_e32 v65, v65, v72
	v_add_f32_e32 v71, 1.0, v71
	v_add_f32_e32 v67, v67, v83
	v_lshlrev_b32_e32 v90, 16, v79
	v_rcp_f32_e32 v66, v66
	v_mul_f32_e32 v67, 0xbfb8aa3b, v67
	v_mul_f32_e32 v70, v66, v90
	v_exp_f32_e32 v67, v67
	s_nop 0
	v_add_f32_e32 v67, 1.0, v67
	v_rcp_f32_e32 v66, v71
	v_and_b32_e32 v77, 0xffff0000, v77
	v_add_u32_e32 v76, 0x80, v148
	v_mul_f32_e32 v66, v66, v77
	v_ashrrev_i32_e32 v77, 31, v76
	v_and_b32_e32 v79, 0xffff0000, v79
	v_rcp_f32_e32 v67, v67
	v_cvt_pk_bf16_f32 v64, v68, v64
	v_cvt_pk_bf16_f32 v65, v65, v66
	v_cvt_pk_bf16_f32 v66, v73, v69
	v_lshlrev_b64 v[68:69], 10, v[76:77]
	v_mul_f32_e32 v67, v67, v79
	v_lshl_add_u64 v[68:69], s[60:61], 0, v[68:69]
	v_cvt_pk_bf16_f32 v67, v70, v67
	v_lshl_add_u64 v[78:79], v[68:69], 0, v[146:147]
	global_store_dwordx4 v[84:85], v[64:67], off offset:1280
	global_load_dwordx4 v[68:71], v[78:79], off
	s_nop 0
	flat_load_dwordx4 v[64:67], v[144:145]
	flat_load_dwordx4 v[72:75], v[144:145] offset:16
	v_lshlrev_b64 v[76:77], 11, v[76:77]
	s_waitcnt vmcnt(0) lgkmcnt(0)
	v_add_f32_e32 v60, v60, v64
	v_mul_f32_e32 v60, 0xbfb8aa3b, v60
	v_exp_f32_e32 v60, v60
	v_add_f32_e32 v56, v56, v72
	v_mul_f32_e32 v56, 0xbfb8aa3b, v56
	v_exp_f32_e32 v56, v56
	v_add_f32_e32 v60, 1.0, v60
	v_add_f32_e32 v56, 1.0, v56
	v_add_f32_e32 v61, v61, v65
	v_mul_f32_e32 v61, 0xbfb8aa3b, v61
	v_rcp_f32_e32 v60, v60
	v_exp_f32_e32 v61, v61
	v_lshlrev_b32_e32 v80, 16, v68
	v_mul_f32_e32 v60, v60, v80
	v_add_f32_e32 v61, 1.0, v61
	v_add_f32_e32 v57, v57, v73
	v_lshlrev_b32_e32 v81, 16, v70
	v_rcp_f32_e32 v56, v56
	v_mul_f32_e32 v57, 0xbfb8aa3b, v57
	v_mul_f32_e32 v65, v56, v81
	v_exp_f32_e32 v57, v57
	s_nop 0
	v_add_f32_e32 v57, 1.0, v57
	v_add_f32_e32 v62, v62, v66
	v_mul_f32_e32 v62, 0xbfb8aa3b, v62
	v_exp_f32_e32 v62, v62
	v_rcp_f32_e32 v56, v61
	v_and_b32_e32 v68, 0xffff0000, v68
	v_mul_f32_e32 v56, v56, v68
	v_add_f32_e32 v62, 1.0, v62
	v_add_f32_e32 v58, v58, v74
	v_and_b32_e32 v70, 0xffff0000, v70
	v_rcp_f32_e32 v57, v57
	v_mul_f32_e32 v58, 0xbfb8aa3b, v58
	v_mul_f32_e32 v61, v57, v70
	v_exp_f32_e32 v58, v58
	s_nop 0
	v_add_f32_e32 v58, 1.0, v58
	v_add_f32_e32 v63, v63, v67
	v_mul_f32_e32 v63, 0xbfb8aa3b, v63
	v_rcp_f32_e32 v57, v62
	v_exp_f32_e32 v63, v63
	v_lshlrev_b32_e32 v64, 16, v69
	v_mul_f32_e32 v57, v57, v64
	v_add_f32_e32 v63, 1.0, v63
	v_add_f32_e32 v59, v59, v75
	v_lshlrev_b32_e32 v84, 16, v71
	v_rcp_f32_e32 v58, v58
	v_mul_f32_e32 v59, 0xbfb8aa3b, v59
	v_mul_f32_e32 v62, v58, v84
	v_exp_f32_e32 v59, v59
	s_nop 0
	v_add_f32_e32 v59, 1.0, v59
	v_rcp_f32_e32 v58, v63
	v_and_b32_e32 v69, 0xffff0000, v69
	v_mul_f32_e32 v58, v58, v69
	v_and_b32_e32 v71, 0xffff0000, v71
	v_rcp_f32_e32 v59, v59
	v_cvt_pk_bf16_f32 v56, v60, v56
	v_cvt_pk_bf16_f32 v57, v57, v58
	v_cvt_pk_bf16_f32 v58, v65, v61
	v_lshl_add_u64 v[60:61], s[48:49], 0, v[76:77]
	v_mul_f32_e32 v59, v59, v71
	v_lshl_add_u64 v[68:69], v[60:61], 0, v[146:147]
	v_cvt_pk_bf16_f32 v59, v62, v59
	global_store_dwordx4 v[68:69], v[56:59], off offset:1024
	global_load_dwordx4 v[60:63], v[78:79], off offset:256
	s_nop 0
	flat_load_dwordx4 v[56:59], v[144:145] offset:512
	flat_load_dwordx4 v[64:67], v[144:145] offset:528
	s_waitcnt vmcnt(0) lgkmcnt(0)
	v_add_f32_e32 v52, v52, v56
	v_mul_f32_e32 v52, 0xbfb8aa3b, v52
	v_exp_f32_e32 v52, v52
	v_add_f32_e32 v48, v48, v64
	v_mul_f32_e32 v48, 0xbfb8aa3b, v48
	v_exp_f32_e32 v48, v48
	v_add_f32_e32 v52, 1.0, v52
	v_add_f32_e32 v48, 1.0, v48
	v_add_f32_e32 v53, v53, v57
	v_mul_f32_e32 v53, 0xbfb8aa3b, v53
	v_rcp_f32_e32 v52, v52
	v_exp_f32_e32 v53, v53
	v_lshlrev_b32_e32 v70, 16, v60
	v_mul_f32_e32 v52, v52, v70
	v_add_f32_e32 v53, 1.0, v53
	v_add_f32_e32 v49, v49, v65
	v_lshlrev_b32_e32 v71, 16, v62
	v_rcp_f32_e32 v48, v48
	v_mul_f32_e32 v49, 0xbfb8aa3b, v49
	v_mul_f32_e32 v57, v48, v71
	v_exp_f32_e32 v49, v49
	s_nop 0
	v_add_f32_e32 v49, 1.0, v49
	v_add_f32_e32 v54, v54, v58
	v_mul_f32_e32 v54, 0xbfb8aa3b, v54
	v_exp_f32_e32 v54, v54
	v_rcp_f32_e32 v48, v53
	v_and_b32_e32 v60, 0xffff0000, v60
	v_mul_f32_e32 v48, v48, v60
	v_add_f32_e32 v54, 1.0, v54
	v_add_f32_e32 v50, v50, v66
	v_and_b32_e32 v62, 0xffff0000, v62
	v_rcp_f32_e32 v49, v49
	v_mul_f32_e32 v50, 0xbfb8aa3b, v50
	v_mul_f32_e32 v53, v49, v62
	v_exp_f32_e32 v50, v50
	s_nop 0
	v_add_f32_e32 v50, 1.0, v50
	v_add_f32_e32 v55, v55, v59
	v_mul_f32_e32 v55, 0xbfb8aa3b, v55
	v_rcp_f32_e32 v49, v54
	v_exp_f32_e32 v55, v55
	v_lshlrev_b32_e32 v56, 16, v61
	v_mul_f32_e32 v49, v49, v56
	v_add_f32_e32 v55, 1.0, v55
	v_add_f32_e32 v51, v51, v67
	v_lshlrev_b32_e32 v74, 16, v63
	v_rcp_f32_e32 v50, v50
	v_mul_f32_e32 v51, 0xbfb8aa3b, v51
	v_mul_f32_e32 v54, v50, v74
	v_exp_f32_e32 v51, v51
	s_nop 0
	v_add_f32_e32 v51, 1.0, v51
	v_rcp_f32_e32 v50, v55
	v_and_b32_e32 v61, 0xffff0000, v61
	v_add_u32_e32 v60, 0x90, v148
	v_mul_f32_e32 v50, v50, v61
	v_ashrrev_i32_e32 v61, 31, v60
	v_and_b32_e32 v63, 0xffff0000, v63
	v_rcp_f32_e32 v51, v51
	v_cvt_pk_bf16_f32 v48, v52, v48
	v_cvt_pk_bf16_f32 v49, v49, v50
	v_cvt_pk_bf16_f32 v50, v57, v53
	v_lshlrev_b64 v[52:53], 10, v[60:61]
	v_mul_f32_e32 v51, v51, v63
	v_lshl_add_u64 v[52:53], s[60:61], 0, v[52:53]
	v_cvt_pk_bf16_f32 v51, v54, v51
	v_lshl_add_u64 v[62:63], v[52:53], 0, v[146:147]
	global_store_dwordx4 v[68:69], v[48:51], off offset:1280
	global_load_dwordx4 v[52:55], v[62:63], off
	s_nop 0
	flat_load_dwordx4 v[48:51], v[144:145]
	flat_load_dwordx4 v[56:59], v[144:145] offset:16
	v_lshlrev_b64 v[60:61], 11, v[60:61]
	s_waitcnt vmcnt(0) lgkmcnt(0)
	v_add_f32_e32 v44, v44, v48
	v_mul_f32_e32 v44, 0xbfb8aa3b, v44
	v_exp_f32_e32 v44, v44
	v_add_f32_e32 v40, v40, v56
	v_mul_f32_e32 v40, 0xbfb8aa3b, v40
	v_exp_f32_e32 v40, v40
	v_add_f32_e32 v44, 1.0, v44
	v_add_f32_e32 v40, 1.0, v40
	v_add_f32_e32 v45, v45, v49
	v_mul_f32_e32 v45, 0xbfb8aa3b, v45
	v_rcp_f32_e32 v44, v44
	v_exp_f32_e32 v45, v45
	v_lshlrev_b32_e32 v64, 16, v52
	v_mul_f32_e32 v44, v44, v64
	v_add_f32_e32 v45, 1.0, v45
	v_add_f32_e32 v41, v41, v57
	v_lshlrev_b32_e32 v65, 16, v54
	v_rcp_f32_e32 v40, v40
	v_mul_f32_e32 v41, 0xbfb8aa3b, v41
	v_mul_f32_e32 v49, v40, v65
	v_exp_f32_e32 v41, v41
	s_nop 0
	v_add_f32_e32 v41, 1.0, v41
	v_add_f32_e32 v46, v46, v50
	v_mul_f32_e32 v46, 0xbfb8aa3b, v46
	v_exp_f32_e32 v46, v46
	v_rcp_f32_e32 v40, v45
	v_and_b32_e32 v52, 0xffff0000, v52
	v_mul_f32_e32 v40, v40, v52
	v_add_f32_e32 v46, 1.0, v46
	v_add_f32_e32 v42, v42, v58
	v_and_b32_e32 v54, 0xffff0000, v54
	v_rcp_f32_e32 v41, v41
	v_mul_f32_e32 v42, 0xbfb8aa3b, v42
	v_mul_f32_e32 v45, v41, v54
	v_exp_f32_e32 v42, v42
	s_nop 0
	v_add_f32_e32 v42, 1.0, v42
	v_add_f32_e32 v47, v47, v51
	v_mul_f32_e32 v47, 0xbfb8aa3b, v47
	v_rcp_f32_e32 v41, v46
	v_exp_f32_e32 v47, v47
	v_lshlrev_b32_e32 v48, 16, v53
	v_mul_f32_e32 v41, v41, v48
	v_add_f32_e32 v47, 1.0, v47
	v_add_f32_e32 v43, v43, v59
	v_lshlrev_b32_e32 v68, 16, v55
	v_rcp_f32_e32 v42, v42
	v_mul_f32_e32 v43, 0xbfb8aa3b, v43
	v_mul_f32_e32 v46, v42, v68
	v_exp_f32_e32 v43, v43
	s_nop 0
	v_add_f32_e32 v43, 1.0, v43
	v_rcp_f32_e32 v42, v47
	v_and_b32_e32 v53, 0xffff0000, v53
	v_mul_f32_e32 v42, v42, v53
	v_and_b32_e32 v55, 0xffff0000, v55
	v_rcp_f32_e32 v43, v43
	v_cvt_pk_bf16_f32 v40, v44, v40
	v_cvt_pk_bf16_f32 v41, v41, v42
	v_cvt_pk_bf16_f32 v42, v49, v45
	v_lshl_add_u64 v[44:45], s[48:49], 0, v[60:61]
	v_mul_f32_e32 v43, v43, v55
	v_lshl_add_u64 v[52:53], v[44:45], 0, v[146:147]
	v_cvt_pk_bf16_f32 v43, v46, v43
	global_store_dwordx4 v[52:53], v[40:43], off offset:1024
	global_load_dwordx4 v[44:47], v[62:63], off offset:256
	s_nop 0
	flat_load_dwordx4 v[40:43], v[144:145] offset:512
	flat_load_dwordx4 v[48:51], v[144:145] offset:528
	s_waitcnt vmcnt(0) lgkmcnt(0)
	v_add_f32_e32 v36, v36, v40
	v_mul_f32_e32 v36, 0xbfb8aa3b, v36
	v_exp_f32_e32 v36, v36
	v_add_f32_e32 v32, v32, v48
	v_mul_f32_e32 v32, 0xbfb8aa3b, v32
	v_exp_f32_e32 v32, v32
	v_add_f32_e32 v36, 1.0, v36
	v_add_f32_e32 v32, 1.0, v32
	v_add_f32_e32 v37, v37, v41
	v_mul_f32_e32 v37, 0xbfb8aa3b, v37
	v_rcp_f32_e32 v36, v36
	v_exp_f32_e32 v37, v37
	v_lshlrev_b32_e32 v54, 16, v44
	v_mul_f32_e32 v36, v36, v54
	v_add_f32_e32 v37, 1.0, v37
	v_add_f32_e32 v33, v33, v49
	v_lshlrev_b32_e32 v55, 16, v46
	v_rcp_f32_e32 v32, v32
	v_mul_f32_e32 v33, 0xbfb8aa3b, v33
	v_mul_f32_e32 v41, v32, v55
	v_exp_f32_e32 v33, v33
	s_nop 0
	v_add_f32_e32 v33, 1.0, v33
	v_add_f32_e32 v38, v38, v42
	v_mul_f32_e32 v38, 0xbfb8aa3b, v38
	v_exp_f32_e32 v38, v38
	v_rcp_f32_e32 v32, v37
	v_and_b32_e32 v44, 0xffff0000, v44
	v_mul_f32_e32 v32, v32, v44
	v_add_f32_e32 v38, 1.0, v38
	v_add_f32_e32 v34, v34, v50
	v_and_b32_e32 v46, 0xffff0000, v46
	v_rcp_f32_e32 v33, v33
	v_mul_f32_e32 v34, 0xbfb8aa3b, v34
	v_mul_f32_e32 v37, v33, v46
	v_exp_f32_e32 v34, v34
	s_nop 0
	v_add_f32_e32 v34, 1.0, v34
	v_add_f32_e32 v39, v39, v43
	v_mul_f32_e32 v39, 0xbfb8aa3b, v39
	v_rcp_f32_e32 v33, v38
	v_exp_f32_e32 v39, v39
	v_lshlrev_b32_e32 v40, 16, v45
	v_mul_f32_e32 v33, v33, v40
	v_add_f32_e32 v39, 1.0, v39
	v_add_f32_e32 v35, v35, v51
	v_lshlrev_b32_e32 v58, 16, v47
	v_rcp_f32_e32 v34, v34
	v_mul_f32_e32 v35, 0xbfb8aa3b, v35
	v_mul_f32_e32 v38, v34, v58
	v_exp_f32_e32 v35, v35
	s_nop 0
	v_add_f32_e32 v35, 1.0, v35
	v_rcp_f32_e32 v34, v39
	v_and_b32_e32 v45, 0xffff0000, v45
	v_add_u32_e32 v44, 0xa0, v148
	v_mul_f32_e32 v34, v34, v45
	v_ashrrev_i32_e32 v45, 31, v44
	v_and_b32_e32 v47, 0xffff0000, v47
	v_rcp_f32_e32 v35, v35
	v_cvt_pk_bf16_f32 v32, v36, v32
	v_cvt_pk_bf16_f32 v33, v33, v34
	v_cvt_pk_bf16_f32 v34, v41, v37
	v_lshlrev_b64 v[36:37], 10, v[44:45]
	v_mul_f32_e32 v35, v35, v47
	v_lshl_add_u64 v[36:37], s[60:61], 0, v[36:37]
	v_cvt_pk_bf16_f32 v35, v38, v35
	v_lshl_add_u64 v[46:47], v[36:37], 0, v[146:147]
	global_store_dwordx4 v[52:53], v[32:35], off offset:1280
	global_load_dwordx4 v[36:39], v[46:47], off
	s_nop 0
	flat_load_dwordx4 v[32:35], v[144:145]
	flat_load_dwordx4 v[40:43], v[144:145] offset:16
	v_lshlrev_b64 v[44:45], 11, v[44:45]
	s_waitcnt vmcnt(0) lgkmcnt(0)
	v_add_f32_e32 v28, v28, v32
	v_mul_f32_e32 v28, 0xbfb8aa3b, v28
	v_exp_f32_e32 v28, v28
	v_add_f32_e32 v24, v24, v40
	v_mul_f32_e32 v24, 0xbfb8aa3b, v24
	v_exp_f32_e32 v24, v24
	v_add_f32_e32 v28, 1.0, v28
	v_add_f32_e32 v24, 1.0, v24
	v_add_f32_e32 v29, v29, v33
	v_mul_f32_e32 v29, 0xbfb8aa3b, v29
	v_rcp_f32_e32 v28, v28
	v_exp_f32_e32 v29, v29
	v_lshlrev_b32_e32 v48, 16, v36
	v_mul_f32_e32 v28, v28, v48
	v_add_f32_e32 v29, 1.0, v29
	v_add_f32_e32 v25, v25, v41
	v_lshlrev_b32_e32 v49, 16, v38
	v_rcp_f32_e32 v24, v24
	v_mul_f32_e32 v25, 0xbfb8aa3b, v25
	v_mul_f32_e32 v33, v24, v49
	v_exp_f32_e32 v25, v25
	s_nop 0
	v_add_f32_e32 v25, 1.0, v25
	v_add_f32_e32 v30, v30, v34
	v_mul_f32_e32 v30, 0xbfb8aa3b, v30
	v_exp_f32_e32 v30, v30
	v_rcp_f32_e32 v24, v29
	v_and_b32_e32 v36, 0xffff0000, v36
	v_mul_f32_e32 v24, v24, v36
	v_add_f32_e32 v30, 1.0, v30
	v_add_f32_e32 v26, v26, v42
	v_and_b32_e32 v38, 0xffff0000, v38
	v_rcp_f32_e32 v25, v25
	v_mul_f32_e32 v26, 0xbfb8aa3b, v26
	v_mul_f32_e32 v29, v25, v38
	v_exp_f32_e32 v26, v26
	s_nop 0
	v_add_f32_e32 v26, 1.0, v26
	v_add_f32_e32 v31, v31, v35
	v_mul_f32_e32 v31, 0xbfb8aa3b, v31
	v_rcp_f32_e32 v25, v30
	v_exp_f32_e32 v31, v31
	v_lshlrev_b32_e32 v32, 16, v37
	v_mul_f32_e32 v25, v25, v32
	v_add_f32_e32 v31, 1.0, v31
	v_add_f32_e32 v27, v27, v43
	v_lshlrev_b32_e32 v52, 16, v39
	v_rcp_f32_e32 v26, v26
	v_mul_f32_e32 v27, 0xbfb8aa3b, v27
	v_mul_f32_e32 v30, v26, v52
	v_exp_f32_e32 v27, v27
	s_nop 0
	v_add_f32_e32 v27, 1.0, v27
	v_rcp_f32_e32 v26, v31
	v_and_b32_e32 v37, 0xffff0000, v37
	v_mul_f32_e32 v26, v26, v37
	v_and_b32_e32 v39, 0xffff0000, v39
	v_rcp_f32_e32 v27, v27
	v_cvt_pk_bf16_f32 v24, v28, v24
	v_cvt_pk_bf16_f32 v25, v25, v26
	v_cvt_pk_bf16_f32 v26, v33, v29
	v_lshl_add_u64 v[28:29], s[48:49], 0, v[44:45]
	v_mul_f32_e32 v27, v27, v39
	v_lshl_add_u64 v[36:37], v[28:29], 0, v[146:147]
	v_cvt_pk_bf16_f32 v27, v30, v27
	global_store_dwordx4 v[36:37], v[24:27], off offset:1024
	global_load_dwordx4 v[28:31], v[46:47], off offset:256
	s_nop 0
	flat_load_dwordx4 v[24:27], v[144:145] offset:512
	flat_load_dwordx4 v[32:35], v[144:145] offset:528
	s_waitcnt vmcnt(0) lgkmcnt(0)
	v_add_f32_e32 v20, v20, v24
	v_mul_f32_e32 v20, 0xbfb8aa3b, v20
	v_exp_f32_e32 v20, v20
	v_add_f32_e32 v16, v16, v32
	v_mul_f32_e32 v16, 0xbfb8aa3b, v16
	v_exp_f32_e32 v16, v16
	v_add_f32_e32 v20, 1.0, v20
	v_add_f32_e32 v16, 1.0, v16
	v_add_f32_e32 v21, v21, v25
	v_mul_f32_e32 v21, 0xbfb8aa3b, v21
	v_rcp_f32_e32 v20, v20
	v_exp_f32_e32 v21, v21
	v_lshlrev_b32_e32 v38, 16, v28
	v_mul_f32_e32 v20, v20, v38
	v_add_f32_e32 v21, 1.0, v21
	v_add_f32_e32 v17, v17, v33
	v_lshlrev_b32_e32 v39, 16, v30
	v_rcp_f32_e32 v16, v16
	v_mul_f32_e32 v17, 0xbfb8aa3b, v17
	v_mul_f32_e32 v25, v16, v39
	v_exp_f32_e32 v17, v17
	s_nop 0
	v_add_f32_e32 v17, 1.0, v17
	v_add_f32_e32 v22, v22, v26
	v_mul_f32_e32 v22, 0xbfb8aa3b, v22
	v_exp_f32_e32 v22, v22
	v_rcp_f32_e32 v16, v21
	v_and_b32_e32 v28, 0xffff0000, v28
	v_mul_f32_e32 v16, v16, v28
	v_add_f32_e32 v22, 1.0, v22
	v_add_f32_e32 v18, v18, v34
	v_and_b32_e32 v30, 0xffff0000, v30
	v_rcp_f32_e32 v17, v17
	v_mul_f32_e32 v18, 0xbfb8aa3b, v18
	v_mul_f32_e32 v21, v17, v30
	v_exp_f32_e32 v18, v18
	s_nop 0
	v_add_f32_e32 v18, 1.0, v18
	v_add_f32_e32 v23, v23, v27
	v_mul_f32_e32 v23, 0xbfb8aa3b, v23
	v_rcp_f32_e32 v17, v22
	v_exp_f32_e32 v23, v23
	v_lshlrev_b32_e32 v24, 16, v29
	v_mul_f32_e32 v17, v17, v24
	v_add_f32_e32 v23, 1.0, v23
	v_add_f32_e32 v19, v19, v35
	v_lshlrev_b32_e32 v42, 16, v31
	v_rcp_f32_e32 v18, v18
	v_mul_f32_e32 v19, 0xbfb8aa3b, v19
	v_mul_f32_e32 v22, v18, v42
	v_exp_f32_e32 v19, v19
	s_nop 0
	v_add_f32_e32 v19, 1.0, v19
	v_rcp_f32_e32 v18, v23
	v_and_b32_e32 v29, 0xffff0000, v29
	v_add_u32_e32 v28, 0xb0, v148
	v_mul_f32_e32 v18, v18, v29
	v_ashrrev_i32_e32 v29, 31, v28
	v_and_b32_e32 v31, 0xffff0000, v31
	v_rcp_f32_e32 v19, v19
	v_cvt_pk_bf16_f32 v16, v20, v16
	v_cvt_pk_bf16_f32 v17, v17, v18
	v_cvt_pk_bf16_f32 v18, v25, v21
	v_lshlrev_b64 v[20:21], 10, v[28:29]
	v_mul_f32_e32 v19, v19, v31
	v_lshl_add_u64 v[20:21], s[60:61], 0, v[20:21]
	v_cvt_pk_bf16_f32 v19, v22, v19
	v_lshl_add_u64 v[30:31], v[20:21], 0, v[146:147]
	global_store_dwordx4 v[36:37], v[16:19], off offset:1280
	global_load_dwordx4 v[20:23], v[30:31], off
	s_nop 0
	flat_load_dwordx4 v[16:19], v[144:145]
	flat_load_dwordx4 v[24:27], v[144:145] offset:16
	v_lshlrev_b64 v[28:29], 11, v[28:29]
	s_waitcnt vmcnt(0) lgkmcnt(0)
	v_add_f32_e32 v12, v12, v16
	v_mul_f32_e32 v12, 0xbfb8aa3b, v12
	v_exp_f32_e32 v12, v12
	v_add_f32_e32 v8, v8, v24
	v_mul_f32_e32 v8, 0xbfb8aa3b, v8
	v_exp_f32_e32 v8, v8
	v_add_f32_e32 v12, 1.0, v12
	v_add_f32_e32 v8, 1.0, v8
	v_add_f32_e32 v13, v13, v17
	v_mul_f32_e32 v13, 0xbfb8aa3b, v13
	v_rcp_f32_e32 v12, v12
	v_exp_f32_e32 v13, v13
	v_lshlrev_b32_e32 v32, 16, v20
	v_mul_f32_e32 v12, v12, v32
	v_add_f32_e32 v13, 1.0, v13
	v_add_f32_e32 v9, v9, v25
	v_lshlrev_b32_e32 v33, 16, v22
	v_rcp_f32_e32 v8, v8
	v_mul_f32_e32 v9, 0xbfb8aa3b, v9
	v_mul_f32_e32 v17, v8, v33
	v_exp_f32_e32 v9, v9
	s_nop 0
	v_add_f32_e32 v9, 1.0, v9
	v_add_f32_e32 v14, v14, v18
	v_mul_f32_e32 v14, 0xbfb8aa3b, v14
	v_exp_f32_e32 v14, v14
	v_rcp_f32_e32 v8, v13
	v_and_b32_e32 v20, 0xffff0000, v20
	v_mul_f32_e32 v8, v8, v20
	v_add_f32_e32 v14, 1.0, v14
	v_add_f32_e32 v10, v10, v26
	v_and_b32_e32 v22, 0xffff0000, v22
	v_rcp_f32_e32 v9, v9
	v_mul_f32_e32 v10, 0xbfb8aa3b, v10
	v_mul_f32_e32 v13, v9, v22
	v_exp_f32_e32 v10, v10
	s_nop 0
	v_add_f32_e32 v10, 1.0, v10
	v_add_f32_e32 v15, v15, v19
	v_mul_f32_e32 v15, 0xbfb8aa3b, v15
	v_rcp_f32_e32 v9, v14
	v_exp_f32_e32 v15, v15
	v_lshlrev_b32_e32 v16, 16, v21
	v_mul_f32_e32 v9, v9, v16
	v_add_f32_e32 v15, 1.0, v15
	v_add_f32_e32 v11, v11, v27
	v_lshlrev_b32_e32 v36, 16, v23
	v_rcp_f32_e32 v10, v10
	v_mul_f32_e32 v11, 0xbfb8aa3b, v11
	v_mul_f32_e32 v14, v10, v36
	v_exp_f32_e32 v11, v11
	s_nop 0
	v_add_f32_e32 v11, 1.0, v11
	v_rcp_f32_e32 v10, v15
	v_and_b32_e32 v21, 0xffff0000, v21
	v_mul_f32_e32 v10, v10, v21
	v_and_b32_e32 v23, 0xffff0000, v23
	v_rcp_f32_e32 v11, v11
	v_cvt_pk_bf16_f32 v8, v12, v8
	v_cvt_pk_bf16_f32 v9, v9, v10
	v_cvt_pk_bf16_f32 v10, v17, v13
	v_lshl_add_u64 v[12:13], s[48:49], 0, v[28:29]
	v_mul_f32_e32 v11, v11, v23
	v_lshl_add_u64 v[20:21], v[12:13], 0, v[146:147]
	v_cvt_pk_bf16_f32 v11, v14, v11
	global_store_dwordx4 v[20:21], v[8:11], off offset:1024
	global_load_dwordx4 v[12:15], v[30:31], off offset:256
	s_nop 0
	flat_load_dwordx4 v[8:11], v[144:145] offset:512
	flat_load_dwordx4 v[16:19], v[144:145] offset:528
	s_waitcnt vmcnt(0) lgkmcnt(0)
	v_add_f32_e32 v4, v4, v8
	v_mul_f32_e32 v4, 0xbfb8aa3b, v4
	v_exp_f32_e32 v4, v4
	v_add_f32_e32 v0, v0, v16
	v_mul_f32_e32 v0, 0xbfb8aa3b, v0
	v_exp_f32_e32 v0, v0
	v_add_f32_e32 v4, 1.0, v4
	v_add_f32_e32 v0, 1.0, v0
	v_add_f32_e32 v5, v5, v9
	v_mul_f32_e32 v5, 0xbfb8aa3b, v5
	v_rcp_f32_e32 v4, v4
	v_exp_f32_e32 v5, v5
	v_lshlrev_b32_e32 v22, 16, v12
	v_mul_f32_e32 v4, v4, v22
	v_add_f32_e32 v5, 1.0, v5
	v_add_f32_e32 v1, v1, v17
	v_lshlrev_b32_e32 v23, 16, v14
	v_rcp_f32_e32 v0, v0
	v_mul_f32_e32 v1, 0xbfb8aa3b, v1
	v_mul_f32_e32 v9, v0, v23
	v_exp_f32_e32 v1, v1
	s_nop 0
	v_add_f32_e32 v1, 1.0, v1
	v_add_f32_e32 v6, v6, v10
	v_mul_f32_e32 v6, 0xbfb8aa3b, v6
	v_exp_f32_e32 v6, v6
	v_rcp_f32_e32 v0, v5
	v_and_b32_e32 v12, 0xffff0000, v12
	v_mul_f32_e32 v0, v0, v12
	v_add_f32_e32 v6, 1.0, v6
	v_add_f32_e32 v2, v2, v18
	v_and_b32_e32 v14, 0xffff0000, v14
	v_rcp_f32_e32 v1, v1
	v_mul_f32_e32 v2, 0xbfb8aa3b, v2
	v_mul_f32_e32 v5, v1, v14
	v_exp_f32_e32 v2, v2
	s_nop 0
	v_add_f32_e32 v2, 1.0, v2
	v_add_f32_e32 v7, v7, v11
	v_mul_f32_e32 v7, 0xbfb8aa3b, v7
	v_rcp_f32_e32 v1, v6
	v_exp_f32_e32 v7, v7
	v_lshlrev_b32_e32 v8, 16, v13
	v_mul_f32_e32 v1, v1, v8
	v_add_f32_e32 v7, 1.0, v7
	v_add_f32_e32 v3, v3, v19
	v_lshlrev_b32_e32 v26, 16, v15
	v_rcp_f32_e32 v2, v2
	v_mul_f32_e32 v3, 0xbfb8aa3b, v3
	v_mul_f32_e32 v6, v2, v26
	v_exp_f32_e32 v3, v3
	s_nop 0
	v_add_f32_e32 v3, 1.0, v3
	v_rcp_f32_e32 v2, v7
	v_and_b32_e32 v13, 0xffff0000, v13
	v_and_b32_e32 v15, 0xffff0000, v15
	v_rcp_f32_e32 v3, v3
	v_mul_f32_e32 v2, v2, v13
	v_mul_f32_e32 v3, v3, v15
	s_andn2_b64 vcc, exec, s[4:5]
	s_mov_b64 s[0:1], -1
	v_cvt_pk_bf16_f32 v0, v4, v0
	v_cvt_pk_bf16_f32 v1, v1, v2
	v_cvt_pk_bf16_f32 v2, v9, v5
	v_cvt_pk_bf16_f32 v3, v6, v3
	global_store_dwordx4 v[20:21], v[0:3], off offset:1280
	s_cbranch_vccnz .LBB0_1424
	s_andn2_b64 vcc, exec, s[14:15]
	s_cbranch_vccnz .LBB0_1423
	s_barrier
	s_branch .LBB0_1423
